# v73 + up-proj epilogue: the 8 serialized row-sum loads issued together with counted waits
# speedup vs baseline: 1.0063x; 1.0063x over previous
; __device__ __forceinline__ unsigned cvt_pk_bf16(float lo, float hi) { unsigned r; asm volatile("v_cvt_pk_bf16_f32 %0, %1, %2" : "=v"(r) : "v"(lo), "v"(hi)); return r; }
;     __device__ __forceinline__ void operator()(const f32x4 (&acc)[2][2][4][2], const Unit& u, int wr, int wc, int fr, int fq) const {
;     ...
; #pragma unroll
;         for (int ai = 0; ai < 2; ++ai)
; #pragma unroll
;             for (int m = 0; m < 4; ++m) {
;                 const int row = row0 + ai * HALF + m * 16; const float rs = 1.0f / sqrtf(__hip_atomic_load(ss2 + row, __ATOMIC_RELAXED, __HIP_MEMORY_SCOPE_AGENT) * (1.0f / 2048.0f) + EPSN);
;                 bf16_t* rowp = H + (size_t)row * DFF + col0;
; #pragma unroll
;                 for (int bj = 0; bj < 2; ++bj) {
;                     f32x4 v0 = acc[ai][bj][m][0] * rs, v1 = acc[ai][bj][m][1] * rs;
; #pragma unroll
;                     for (int j = 0; j < 4; ++j) { v0[j] = fmaxf(v0[j], 0.f); v0[j] *= v0[j]; v1[j] = fmaxf(v1[j], 0.f); v1[j] *= v1[j]; }
;                     u32x4 w; w.x = cvt_pk_bf16(v0[0], v0[1]); w.y = cvt_pk_bf16(v0[2], v0[3]); w.z = cvt_pk_bf16(v1[0], v1[1]); w.w = cvt_pk_bf16(v1[2], v1[3]);
;                     *(u32x4*)(rowp + bj * HALF) = w;
.LBB0_864:
	v_lshl_add_u32 v150, s4, 8, v152
	v_ashrrev_i32_e32 v151, 31, v150
	v_lshl_add_u64 v[144:145], v[150:151], 2, s[38:39]
	global_load_dword v161, v[144:145], off sc1
	global_load_dword v228, v[144:145], off offset:64 sc1
	global_load_dword v229, v[144:145], off offset:128 sc1
	global_load_dword v230, v[144:145], off offset:192 sc1
	global_load_dword v231, v[144:145], off offset:512 sc1
	global_load_dword v232, v[144:145], off offset:576 sc1
	global_load_dword v233, v[144:145], off offset:640 sc1
	global_load_dword v234, v[144:145], off offset:704 sc1
	v_lshl_or_b32 v146, s0, 8, v154
	v_ashrrev_i32_e32 v147, 31, v146
	v_lshlrev_b64 v[148:149], 1, v[146:147]
	v_lshlrev_b64 v[164:165], 14, v[150:151]
	v_or_b32_e32 v162, 16, v150
	v_ashrrev_i32_e32 v163, 31, v162
	s_waitcnt vmcnt(7)
	v_fmamk_f32 v146, v161, 0x3a000000, v158
	v_mul_f32_e32 v147, 0x4f800000, v146
	v_cmp_gt_f32_e32 vcc, s75, v146
	s_nop 1
	v_cndmask_b32_e32 v151, v146, v147, vcc
	v_sqrt_f32_e32 v161, v151
	v_lshl_add_u64 v[146:147], s[10:11], 0, v[164:165]
	v_lshl_add_u64 v[146:147], v[146:147], 0, v[148:149]
	v_lshl_add_u64 v[164:165], v[162:163], 2, s[38:39]
	v_add_u32_e32 v166, -1, v161
	v_add_u32_e32 v167, 1, v161
	v_fma_f32 v168, -v166, v161, v151
	v_fma_f32 v169, -v167, v161, v151
	v_cmp_ge_f32_e64 s[4:5], 0, v168
	s_nop 1
	v_cndmask_b32_e64 v161, v161, v166, s[4:5]
	v_cmp_lt_f32_e64 s[4:5], 0, v169
	s_nop 1
	v_cndmask_b32_e64 v161, v161, v167, s[4:5]
	v_mul_f32_e32 v166, 0x37800000, v161
	v_cndmask_b32_e32 v161, v161, v166, vcc
	v_cmp_class_f32_e32 vcc, v151, v159
	s_nop 1
	v_cndmask_b32_e32 v151, v161, v151, vcc
	v_div_scale_f32 v161, s[0:1], v151, v151, 1.0
	v_rcp_f32_e32 v166, v161
	v_div_scale_f32 v167, vcc, 1.0, v151, 1.0
	v_fma_f32 v168, -v161, v166, 1.0
	v_fmac_f32_e32 v166, v168, v166
	v_mul_f32_e32 v168, v167, v166
	v_fma_f32 v169, -v161, v168, v167
	v_fmac_f32_e32 v168, v169, v166
	v_fma_f32 v161, -v161, v168, v167
	v_div_fmas_f32 v161, v161, v166, v168
	v_div_fixup_f32 v166, v161, v151, 1.0
	v_pk_mul_f32 v[126:127], v[126:127], v[166:167] op_sel_hi:[1,0]
	v_pk_mul_f32 v[124:125], v[124:125], v[166:167] op_sel_hi:[1,0]
	v_pk_mul_f32 v[122:123], v[122:123], v[166:167] op_sel_hi:[1,0]
	v_pk_mul_f32 v[120:121], v[120:121], v[166:167] op_sel_hi:[1,0]
	v_pk_mul_f32 v[114:115], v[114:115], v[166:167] op_sel_hi:[1,0]
	v_pk_mul_f32 v[112:113], v[112:113], v[166:167] op_sel_hi:[1,0]
	v_pk_mul_f32 v[118:119], v[118:119], v[166:167] op_sel_hi:[1,0]
	v_pk_mul_f32 v[116:117], v[116:117], v[166:167] op_sel_hi:[1,0]
	v_max_f32_e32 v124, 0, v124
	v_max_f32_e32 v120, 0, v120
	v_max_f32_e32 v125, 0, v125
	v_max_f32_e32 v121, 0, v121
	v_max_f32_e32 v126, 0, v126
	v_max_f32_e32 v122, 0, v122
	v_max_f32_e32 v127, 0, v127
	v_max_f32_e32 v123, 0, v123
	v_max_f32_e32 v112, 0, v112
	v_max_f32_e32 v113, 0, v113
	v_max_f32_e32 v114, 0, v114
	v_max_f32_e32 v115, 0, v115
	v_max_f32_e32 v116, 0, v116
	v_max_f32_e32 v117, 0, v117
	v_max_f32_e32 v118, 0, v118
	v_max_f32_e32 v119, 0, v119
	v_mul_f32_e32 v124, v124, v124
	v_mul_f32_e32 v120, v120, v120
	v_mul_f32_e32 v125, v125, v125
	v_mul_f32_e32 v121, v121, v121
	v_mul_f32_e32 v126, v126, v126
	v_mul_f32_e32 v122, v122, v122
	v_mul_f32_e32 v127, v127, v127
	v_mul_f32_e32 v123, v123, v123
	v_mul_f32_e32 v151, v112, v112
	v_mul_f32_e32 v161, v113, v113
	v_mul_f32_e32 v166, v114, v114
	v_mul_f32_e32 v167, v115, v115
	v_cvt_pk_bf16_f32 v112, v124, v125
	v_cvt_pk_bf16_f32 v113, v126, v127
	v_cvt_pk_bf16_f32 v114, v120, v121
	v_cvt_pk_bf16_f32 v115, v122, v123
	v_mul_f32_e32 v116, v116, v116
	v_mul_f32_e32 v117, v117, v117
	v_mul_f32_e32 v118, v118, v118
	v_mul_f32_e32 v119, v119, v119
	global_store_dwordx4 v[146:147], v[112:115], off
	s_nop 1
	v_cvt_pk_bf16_f32 v112, v116, v117
	v_cvt_pk_bf16_f32 v113, v118, v119
	v_cvt_pk_bf16_f32 v114, v151, v161
	v_cvt_pk_bf16_f32 v115, v166, v167
	global_store_dwordx4 v[146:147], v[112:115], off offset:256
	s_nop 0
	s_nop 0
	v_or_b32_e32 v112, 32, v150
	v_ashrrev_i32_e32 v113, 31, v112
	v_lshl_add_u64 v[116:117], v[112:113], 2, s[38:39]
	s_waitcnt vmcnt(8)
	v_fmamk_f32 v114, v228, 0x3a000000, v158
	v_mul_f32_e32 v115, 0x4f800000, v114
	v_cmp_gt_f32_e32 vcc, s75, v114
	s_nop 1
	v_cndmask_b32_e32 v118, v114, v115, vcc
	v_sqrt_f32_e32 v119, v118
	v_lshlrev_b64 v[114:115], 14, v[162:163]
	v_lshl_add_u64 v[114:115], s[10:11], 0, v[114:115]
	v_lshl_add_u64 v[114:115], v[114:115], 0, v[148:149]
	v_add_u32_e32 v120, -1, v119
	v_add_u32_e32 v121, 1, v119
	v_fma_f32 v122, -v120, v119, v118
	v_fma_f32 v123, -v121, v119, v118
	v_cmp_ge_f32_e64 s[4:5], 0, v122
	s_nop 1
	v_cndmask_b32_e64 v119, v119, v120, s[4:5]
	v_cmp_lt_f32_e64 s[4:5], 0, v123
	s_nop 1
	v_cndmask_b32_e64 v119, v119, v121, s[4:5]
	v_mul_f32_e32 v120, 0x37800000, v119
	v_cndmask_b32_e32 v119, v119, v120, vcc
	v_cmp_class_f32_e32 vcc, v118, v159
	s_nop 1
	v_cndmask_b32_e32 v118, v119, v118, vcc
	v_div_scale_f32 v119, s[0:1], v118, v118, 1.0
	v_rcp_f32_e32 v120, v119
	v_div_scale_f32 v121, vcc, 1.0, v118, 1.0
	v_fma_f32 v122, -v119, v120, 1.0
	v_fmac_f32_e32 v120, v122, v120
	v_mul_f32_e32 v122, v121, v120
	v_fma_f32 v123, -v119, v122, v121
	v_fmac_f32_e32 v122, v123, v120
	v_fma_f32 v119, -v119, v122, v121
	v_div_fmas_f32 v119, v119, v120, v122
	v_div_fixup_f32 v118, v119, v118, 1.0
	v_pk_mul_f32 v[110:111], v[110:111], v[118:119] op_sel_hi:[1,0]
	v_pk_mul_f32 v[108:109], v[108:109], v[118:119] op_sel_hi:[1,0]
	v_pk_mul_f32 v[106:107], v[106:107], v[118:119] op_sel_hi:[1,0]
	v_pk_mul_f32 v[104:105], v[104:105], v[118:119] op_sel_hi:[1,0]
	v_pk_mul_f32 v[98:99], v[98:99], v[118:119] op_sel_hi:[1,0]
	v_pk_mul_f32 v[96:97], v[96:97], v[118:119] op_sel_hi:[1,0]
; __device__ __forceinline__ unsigned cvt_pk_bf16(float lo, float hi) { unsigned r; asm volatile("v_cvt_pk_bf16_f32 %0, %1, %2" : "=v"(r) : "v"(lo), "v"(hi)); return r; }
;     __device__ __forceinline__ void operator()(const f32x4 (&acc)[2][2][4][2], const Unit& u, int wr, int wc, int fr, int fq) const {
;     ...
; #pragma unroll
;         for (int ai = 0; ai < 2; ++ai)
; #pragma unroll
;             for (int m = 0; m < 4; ++m) {
;                 const int row = row0 + ai * HALF + m * 16; const float rs = 1.0f / sqrtf(__hip_atomic_load(ss2 + row, __ATOMIC_RELAXED, __HIP_MEMORY_SCOPE_AGENT) * (1.0f / 2048.0f) + EPSN);
;                 bf16_t* rowp = H + (size_t)row * DFF + col0;
; #pragma unroll
;                 for (int bj = 0; bj < 2; ++bj) {
;                     f32x4 v0 = acc[ai][bj][m][0] * rs, v1 = acc[ai][bj][m][1] * rs;
; #pragma unroll
;                     for (int j = 0; j < 4; ++j) { v0[j] = fmaxf(v0[j], 0.f); v0[j] *= v0[j]; v1[j] = fmaxf(v1[j], 0.f); v1[j] *= v1[j]; }
;                     u32x4 w; w.x = cvt_pk_bf16(v0[0], v0[1]); w.y = cvt_pk_bf16(v0[2], v0[3]); w.z = cvt_pk_bf16(v1[0], v1[1]); w.w = cvt_pk_bf16(v1[2], v1[3]);
;                     *(u32x4*)(rowp + bj * HALF) = w;
	v_pk_mul_f32 v[102:103], v[102:103], v[118:119] op_sel_hi:[1,0]
	v_pk_mul_f32 v[100:101], v[100:101], v[118:119] op_sel_hi:[1,0]
	v_max_f32_e32 v108, 0, v108
	v_max_f32_e32 v104, 0, v104
	v_max_f32_e32 v109, 0, v109
	v_max_f32_e32 v105, 0, v105
	v_max_f32_e32 v110, 0, v110
	v_max_f32_e32 v106, 0, v106
	v_max_f32_e32 v111, 0, v111
	v_max_f32_e32 v107, 0, v107
	v_max_f32_e32 v96, 0, v96
	v_max_f32_e32 v97, 0, v97
	v_max_f32_e32 v98, 0, v98
	v_max_f32_e32 v99, 0, v99
	v_max_f32_e32 v100, 0, v100
	v_max_f32_e32 v101, 0, v101
	v_max_f32_e32 v102, 0, v102
	v_max_f32_e32 v103, 0, v103
	v_mul_f32_e32 v108, v108, v108
	v_mul_f32_e32 v104, v104, v104
	v_mul_f32_e32 v109, v109, v109
	v_mul_f32_e32 v105, v105, v105
	v_mul_f32_e32 v110, v110, v110
	v_mul_f32_e32 v106, v106, v106
	v_mul_f32_e32 v111, v111, v111
	v_mul_f32_e32 v107, v107, v107
	v_mul_f32_e32 v118, v96, v96
	v_mul_f32_e32 v119, v97, v97
	v_mul_f32_e32 v120, v98, v98
	v_mul_f32_e32 v121, v99, v99
	v_cvt_pk_bf16_f32 v96, v108, v109
	v_cvt_pk_bf16_f32 v97, v110, v111
	v_cvt_pk_bf16_f32 v98, v104, v105
	v_cvt_pk_bf16_f32 v99, v106, v107
	v_mul_f32_e32 v100, v100, v100
	v_mul_f32_e32 v101, v101, v101
	v_mul_f32_e32 v102, v102, v102
	v_mul_f32_e32 v103, v103, v103
	global_store_dwordx4 v[114:115], v[96:99], off
	s_nop 1
	v_cvt_pk_bf16_f32 v96, v100, v101
	v_cvt_pk_bf16_f32 v97, v102, v103
	v_cvt_pk_bf16_f32 v98, v118, v119
	v_cvt_pk_bf16_f32 v99, v120, v121
	global_store_dwordx4 v[114:115], v[96:99], off offset:256
	s_nop 0
	s_nop 0
	v_or_b32_e32 v96, 48, v150
	v_ashrrev_i32_e32 v97, 31, v96
	v_lshl_add_u64 v[100:101], v[96:97], 2, s[38:39]
	s_waitcnt vmcnt(9)
	v_fmamk_f32 v98, v229, 0x3a000000, v158
	v_mul_f32_e32 v99, 0x4f800000, v98
	v_cmp_gt_f32_e32 vcc, s75, v98
	s_nop 1
	v_cndmask_b32_e32 v102, v98, v99, vcc
	v_sqrt_f32_e32 v103, v102
	v_lshlrev_b64 v[98:99], 14, v[112:113]
	v_lshl_add_u64 v[98:99], s[10:11], 0, v[98:99]
	v_lshl_add_u64 v[98:99], v[98:99], 0, v[148:149]
	v_add_u32_e32 v104, -1, v103
	v_add_u32_e32 v105, 1, v103
	v_fma_f32 v106, -v104, v103, v102
	v_fma_f32 v107, -v105, v103, v102
	v_cmp_ge_f32_e64 s[4:5], 0, v106
	s_nop 1
	v_cndmask_b32_e64 v103, v103, v104, s[4:5]
	v_cmp_lt_f32_e64 s[4:5], 0, v107
	s_nop 1
	v_cndmask_b32_e64 v103, v103, v105, s[4:5]
	v_mul_f32_e32 v104, 0x37800000, v103
	v_cndmask_b32_e32 v103, v103, v104, vcc
	v_cmp_class_f32_e32 vcc, v102, v159
	s_nop 1
	v_cndmask_b32_e32 v102, v103, v102, vcc
	v_div_scale_f32 v103, s[0:1], v102, v102, 1.0
	v_rcp_f32_e32 v104, v103
	v_div_scale_f32 v105, vcc, 1.0, v102, 1.0
	v_fma_f32 v106, -v103, v104, 1.0
	v_fmac_f32_e32 v104, v106, v104
	v_mul_f32_e32 v106, v105, v104
	v_fma_f32 v107, -v103, v106, v105
	v_fmac_f32_e32 v106, v107, v104
	v_fma_f32 v103, -v103, v106, v105
	v_div_fmas_f32 v103, v103, v104, v106
	v_div_fixup_f32 v102, v103, v102, 1.0
	v_pk_mul_f32 v[94:95], v[94:95], v[102:103] op_sel_hi:[1,0]
	v_pk_mul_f32 v[92:93], v[92:93], v[102:103] op_sel_hi:[1,0]
	v_pk_mul_f32 v[90:91], v[90:91], v[102:103] op_sel_hi:[1,0]
	v_pk_mul_f32 v[88:89], v[88:89], v[102:103] op_sel_hi:[1,0]
	v_pk_mul_f32 v[82:83], v[82:83], v[102:103] op_sel_hi:[1,0]
	v_pk_mul_f32 v[80:81], v[80:81], v[102:103] op_sel_hi:[1,0]
	v_pk_mul_f32 v[86:87], v[86:87], v[102:103] op_sel_hi:[1,0]
	v_pk_mul_f32 v[84:85], v[84:85], v[102:103] op_sel_hi:[1,0]
	v_max_f32_e32 v92, 0, v92
	v_max_f32_e32 v88, 0, v88
	v_max_f32_e32 v93, 0, v93
	v_max_f32_e32 v89, 0, v89
	v_max_f32_e32 v94, 0, v94
	v_max_f32_e32 v90, 0, v90
	v_max_f32_e32 v95, 0, v95
	v_max_f32_e32 v91, 0, v91
	v_max_f32_e32 v80, 0, v80
	v_max_f32_e32 v81, 0, v81
	v_max_f32_e32 v82, 0, v82
	v_max_f32_e32 v83, 0, v83
	v_max_f32_e32 v84, 0, v84
	v_max_f32_e32 v85, 0, v85
	v_max_f32_e32 v86, 0, v86
	v_max_f32_e32 v87, 0, v87
	v_mul_f32_e32 v92, v92, v92
	v_mul_f32_e32 v88, v88, v88
	v_mul_f32_e32 v93, v93, v93
	v_mul_f32_e32 v89, v89, v89
	v_mul_f32_e32 v94, v94, v94
	v_mul_f32_e32 v90, v90, v90
	v_mul_f32_e32 v95, v95, v95
	v_mul_f32_e32 v91, v91, v91
	v_mul_f32_e32 v102, v80, v80
	v_mul_f32_e32 v103, v81, v81
	v_mul_f32_e32 v104, v82, v82
	v_mul_f32_e32 v105, v83, v83
	v_cvt_pk_bf16_f32 v80, v92, v93
	v_cvt_pk_bf16_f32 v81, v94, v95
	v_cvt_pk_bf16_f32 v82, v88, v89
	v_cvt_pk_bf16_f32 v83, v90, v91
	v_mul_f32_e32 v84, v84, v84
	v_mul_f32_e32 v85, v85, v85
	v_mul_f32_e32 v86, v86, v86
	v_mul_f32_e32 v87, v87, v87
	global_store_dwordx4 v[98:99], v[80:83], off
	s_nop 1
	v_cvt_pk_bf16_f32 v80, v84, v85
	v_cvt_pk_bf16_f32 v81, v86, v87
	v_cvt_pk_bf16_f32 v82, v102, v103
	v_cvt_pk_bf16_f32 v83, v104, v105
	global_store_dwordx4 v[98:99], v[80:83], off offset:256
	s_nop 0
	s_waitcnt vmcnt(10)
; __device__ __forceinline__ unsigned cvt_pk_bf16(float lo, float hi) { unsigned r; asm volatile("v_cvt_pk_bf16_f32 %0, %1, %2" : "=v"(r) : "v"(lo), "v"(hi)); return r; }
;     __device__ __forceinline__ void operator()(const f32x4 (&acc)[2][2][4][2], const Unit& u, int wr, int wc, int fr, int fq) const {
;     ...
; #pragma unroll
;         for (int ai = 0; ai < 2; ++ai)
; #pragma unroll
;             for (int m = 0; m < 4; ++m) {
;                 const int row = row0 + ai * HALF + m * 16; const float rs = 1.0f / sqrtf(__hip_atomic_load(ss2 + row, __ATOMIC_RELAXED, __HIP_MEMORY_SCOPE_AGENT) * (1.0f / 2048.0f) + EPSN);
;                 bf16_t* rowp = H + (size_t)row * DFF + col0;
; #pragma unroll
;                 for (int bj = 0; bj < 2; ++bj) {
;                     f32x4 v0 = acc[ai][bj][m][0] * rs, v1 = acc[ai][bj][m][1] * rs;
; #pragma unroll
;                     for (int j = 0; j < 4; ++j) { v0[j] = fmaxf(v0[j], 0.f); v0[j] *= v0[j]; v1[j] = fmaxf(v1[j], 0.f); v1[j] *= v1[j]; }
;                     u32x4 w; w.x = cvt_pk_bf16(v0[0], v0[1]); w.y = cvt_pk_bf16(v0[2], v0[3]); w.z = cvt_pk_bf16(v1[0], v1[1]); w.w = cvt_pk_bf16(v1[2], v1[3]);
;                     *(u32x4*)(rowp + bj * HALF) = w;
	v_fmamk_f32 v80, v230, 0x3a000000, v158
	v_mul_f32_e32 v81, 0x4f800000, v80
	v_cmp_gt_f32_e32 vcc, s75, v80
	s_nop 1
	v_cndmask_b32_e32 v82, v80, v81, vcc
	v_sqrt_f32_e32 v83, v82
	v_lshlrev_b64 v[80:81], 14, v[96:97]
	v_lshl_add_u64 v[80:81], s[10:11], 0, v[80:81]
	v_lshl_add_u64 v[80:81], v[80:81], 0, v[148:149]
	v_add_u32_e32 v84, -1, v83
	v_add_u32_e32 v85, 1, v83
	v_fma_f32 v86, -v84, v83, v82
	v_fma_f32 v87, -v85, v83, v82
	v_cmp_ge_f32_e64 s[4:5], 0, v86
	s_nop 1
	v_cndmask_b32_e64 v83, v83, v84, s[4:5]
	v_cmp_lt_f32_e64 s[4:5], 0, v87
	s_nop 1
	v_cndmask_b32_e64 v83, v83, v85, s[4:5]
	v_mul_f32_e32 v84, 0x37800000, v83
	v_cndmask_b32_e32 v83, v83, v84, vcc
	v_cmp_class_f32_e32 vcc, v82, v159
	s_nop 1
	v_cndmask_b32_e32 v82, v83, v82, vcc
	v_div_scale_f32 v83, s[0:1], v82, v82, 1.0
	v_rcp_f32_e32 v84, v83
	v_div_scale_f32 v85, vcc, 1.0, v82, 1.0
	v_fma_f32 v86, -v83, v84, 1.0
	v_fmac_f32_e32 v84, v86, v84
	v_mul_f32_e32 v86, v85, v84
	v_fma_f32 v87, -v83, v86, v85
	v_fmac_f32_e32 v86, v87, v84
	v_fma_f32 v83, -v83, v86, v85
	v_div_fmas_f32 v83, v83, v84, v86
	v_div_fixup_f32 v82, v83, v82, 1.0
	v_pk_mul_f32 v[78:79], v[78:79], v[82:83] op_sel_hi:[1,0]
	v_pk_mul_f32 v[76:77], v[76:77], v[82:83] op_sel_hi:[1,0]
	v_pk_mul_f32 v[74:75], v[74:75], v[82:83] op_sel_hi:[1,0]
	v_pk_mul_f32 v[72:73], v[72:73], v[82:83] op_sel_hi:[1,0]
	v_pk_mul_f32 v[66:67], v[66:67], v[82:83] op_sel_hi:[1,0]
	v_pk_mul_f32 v[64:65], v[64:65], v[82:83] op_sel_hi:[1,0]
	v_pk_mul_f32 v[70:71], v[70:71], v[82:83] op_sel_hi:[1,0]
	v_pk_mul_f32 v[68:69], v[68:69], v[82:83] op_sel_hi:[1,0]
	v_max_f32_e32 v76, 0, v76
	v_max_f32_e32 v72, 0, v72
	v_max_f32_e32 v77, 0, v77
	v_max_f32_e32 v73, 0, v73
	v_max_f32_e32 v78, 0, v78
	v_max_f32_e32 v74, 0, v74
	v_max_f32_e32 v79, 0, v79
	v_max_f32_e32 v75, 0, v75
	v_max_f32_e32 v64, 0, v64
	v_max_f32_e32 v65, 0, v65
	v_max_f32_e32 v66, 0, v66
	v_max_f32_e32 v67, 0, v67
	v_max_f32_e32 v68, 0, v68
	v_max_f32_e32 v69, 0, v69
	v_max_f32_e32 v70, 0, v70
	v_max_f32_e32 v71, 0, v71
	v_mul_f32_e32 v76, v76, v76
	v_mul_f32_e32 v72, v72, v72
	v_mul_f32_e32 v77, v77, v77
	v_mul_f32_e32 v73, v73, v73
	v_mul_f32_e32 v78, v78, v78
	v_mul_f32_e32 v74, v74, v74
	v_mul_f32_e32 v79, v79, v79
	v_mul_f32_e32 v75, v75, v75
	v_mul_f32_e32 v82, v64, v64
	v_mul_f32_e32 v83, v65, v65
	v_mul_f32_e32 v84, v66, v66
	v_mul_f32_e32 v85, v67, v67
	v_cvt_pk_bf16_f32 v64, v76, v77
	v_cvt_pk_bf16_f32 v65, v78, v79
	v_cvt_pk_bf16_f32 v66, v72, v73
	v_cvt_pk_bf16_f32 v67, v74, v75
	v_mul_f32_e32 v68, v68, v68
	v_mul_f32_e32 v69, v69, v69
	v_mul_f32_e32 v70, v70, v70
	v_mul_f32_e32 v71, v71, v71
	global_store_dwordx4 v[80:81], v[64:67], off
	s_nop 1
	v_cvt_pk_bf16_f32 v64, v68, v69
	v_cvt_pk_bf16_f32 v65, v70, v71
	v_cvt_pk_bf16_f32 v66, v82, v83
	v_cvt_pk_bf16_f32 v67, v84, v85
	global_store_dwordx4 v[80:81], v[64:67], off offset:256
	s_nop 0
	s_waitcnt vmcnt(11)
	v_fmamk_f32 v64, v231, 0x3a000000, v158
	v_mul_f32_e32 v65, 0x4f800000, v64
	v_cmp_gt_f32_e32 vcc, s75, v64
	s_nop 1
	v_cndmask_b32_e32 v66, v64, v65, vcc
	v_sqrt_f32_e32 v67, v66
	v_lshl_add_u64 v[64:65], v[146:147], 0, s[40:41]
	v_add_u32_e32 v68, -1, v67
	v_add_u32_e32 v69, 1, v67
	v_fma_f32 v70, -v68, v67, v66
	v_fma_f32 v71, -v69, v67, v66
	v_cmp_ge_f32_e64 s[4:5], 0, v70
	s_nop 1
	v_cndmask_b32_e64 v67, v67, v68, s[4:5]
	v_cmp_lt_f32_e64 s[4:5], 0, v71
	s_nop 1
	v_cndmask_b32_e64 v67, v67, v69, s[4:5]
	v_mul_f32_e32 v68, 0x37800000, v67
	v_cndmask_b32_e32 v67, v67, v68, vcc
	v_cmp_class_f32_e32 vcc, v66, v159
	s_nop 1
	v_cndmask_b32_e32 v68, v67, v66, vcc
	v_div_scale_f32 v69, s[0:1], v68, v68, 1.0
	v_rcp_f32_e32 v70, v69
	v_add_co_u32_e32 v66, vcc, s76, v146
	v_fma_f32 v72, -v69, v70, 1.0
	s_nop 0
	v_addc_co_u32_e32 v67, vcc, 0, v147, vcc
	v_div_scale_f32 v71, vcc, 1.0, v68, 1.0
	v_fmac_f32_e32 v70, v72, v70
	v_mul_f32_e32 v72, v71, v70
	v_fma_f32 v73, -v69, v72, v71
	v_fmac_f32_e32 v72, v73, v70
	v_fma_f32 v69, -v69, v72, v71
	v_div_fmas_f32 v69, v69, v70, v72
	v_div_fixup_f32 v68, v69, v68, 1.0
	v_pk_mul_f32 v[62:63], v[62:63], v[68:69] op_sel_hi:[1,0]
	v_pk_mul_f32 v[60:61], v[60:61], v[68:69] op_sel_hi:[1,0]
	v_pk_mul_f32 v[58:59], v[58:59], v[68:69] op_sel_hi:[1,0]
	v_pk_mul_f32 v[56:57], v[56:57], v[68:69] op_sel_hi:[1,0]
	v_pk_mul_f32 v[50:51], v[50:51], v[68:69] op_sel_hi:[1,0]
	v_pk_mul_f32 v[48:49], v[48:49], v[68:69] op_sel_hi:[1,0]
	v_pk_mul_f32 v[54:55], v[54:55], v[68:69] op_sel_hi:[1,0]
	v_pk_mul_f32 v[52:53], v[52:53], v[68:69] op_sel_hi:[1,0]
	v_max_f32_e32 v60, 0, v60
	v_max_f32_e32 v56, 0, v56
	v_max_f32_e32 v61, 0, v61
	v_max_f32_e32 v57, 0, v57
	v_max_f32_e32 v62, 0, v62
	v_max_f32_e32 v58, 0, v58
	v_max_f32_e32 v63, 0, v63
	v_max_f32_e32 v59, 0, v59
	v_max_f32_e32 v48, 0, v48
	v_max_f32_e32 v49, 0, v49
	v_max_f32_e32 v50, 0, v50
	v_max_f32_e32 v51, 0, v51
	v_max_f32_e32 v52, 0, v52
	v_max_f32_e32 v53, 0, v53
	v_max_f32_e32 v54, 0, v54
	v_max_f32_e32 v55, 0, v55
	v_mul_f32_e32 v60, v60, v60
	v_mul_f32_e32 v56, v56, v56
	v_mul_f32_e32 v61, v61, v61
	v_mul_f32_e32 v57, v57, v57
	v_mul_f32_e32 v62, v62, v62
	v_mul_f32_e32 v58, v58, v58
	v_mul_f32_e32 v63, v63, v63
	v_mul_f32_e32 v59, v59, v59
	v_mul_f32_e32 v68, v48, v48
	v_mul_f32_e32 v69, v49, v49
	v_mul_f32_e32 v70, v50, v50
	v_mul_f32_e32 v71, v51, v51
	v_cvt_pk_bf16_f32 v48, v60, v61
	v_cvt_pk_bf16_f32 v49, v62, v63
	v_cvt_pk_bf16_f32 v50, v56, v57
	v_cvt_pk_bf16_f32 v51, v58, v59
	v_mul_f32_e32 v52, v52, v52
	v_mul_f32_e32 v53, v53, v53
	v_mul_f32_e32 v54, v54, v54
	v_mul_f32_e32 v55, v55, v55
	global_store_dwordx4 v[66:67], v[48:51], off
	s_nop 1
	v_cvt_pk_bf16_f32 v48, v52, v53
	v_cvt_pk_bf16_f32 v49, v54, v55
	v_cvt_pk_bf16_f32 v50, v68, v69
	v_cvt_pk_bf16_f32 v51, v70, v71
	global_store_dwordx4 v[64:65], v[48:51], off offset:256
	s_nop 0
	s_waitcnt vmcnt(12)
; __device__ __forceinline__ unsigned cvt_pk_bf16(float lo, float hi) { unsigned r; asm volatile("v_cvt_pk_bf16_f32 %0, %1, %2" : "=v"(r) : "v"(lo), "v"(hi)); return r; }
;     __device__ __forceinline__ void operator()(const f32x4 (&acc)[2][2][4][2], const Unit& u, int wr, int wc, int fr, int fq) const {
;     ...
; #pragma unroll
;         for (int ai = 0; ai < 2; ++ai)
; #pragma unroll
;             for (int m = 0; m < 4; ++m) {
;                 const int row = row0 + ai * HALF + m * 16; const float rs = 1.0f / sqrtf(__hip_atomic_load(ss2 + row, __ATOMIC_RELAXED, __HIP_MEMORY_SCOPE_AGENT) * (1.0f / 2048.0f) + EPSN);
;                 bf16_t* rowp = H + (size_t)row * DFF + col0;
; #pragma unroll
;                 for (int bj = 0; bj < 2; ++bj) {
;                     f32x4 v0 = acc[ai][bj][m][0] * rs, v1 = acc[ai][bj][m][1] * rs;
; #pragma unroll
;                     for (int j = 0; j < 4; ++j) { v0[j] = fmaxf(v0[j], 0.f); v0[j] *= v0[j]; v1[j] = fmaxf(v1[j], 0.f); v1[j] *= v1[j]; }
;                     u32x4 w; w.x = cvt_pk_bf16(v0[0], v0[1]); w.y = cvt_pk_bf16(v0[2], v0[3]); w.z = cvt_pk_bf16(v1[0], v1[1]); w.w = cvt_pk_bf16(v1[2], v1[3]);
;                     *(u32x4*)(rowp + bj * HALF) = w;
	v_fmamk_f32 v48, v232, 0x3a000000, v158
	v_mul_f32_e32 v49, 0x4f800000, v48
	v_cmp_gt_f32_e32 vcc, s75, v48
	s_nop 1
	v_cndmask_b32_e32 v50, v48, v49, vcc
	v_sqrt_f32_e32 v51, v50
	v_lshl_add_u64 v[48:49], v[146:147], 0, s[42:43]
	v_add_u32_e32 v52, -1, v51
	v_add_u32_e32 v53, 1, v51
	v_fma_f32 v54, -v52, v51, v50
	v_fma_f32 v55, -v53, v51, v50
	v_cmp_ge_f32_e64 s[4:5], 0, v54
	s_nop 1
	v_cndmask_b32_e64 v51, v51, v52, s[4:5]
	v_cmp_lt_f32_e64 s[4:5], 0, v55
	s_nop 1
	v_cndmask_b32_e64 v51, v51, v53, s[4:5]
	v_mul_f32_e32 v52, 0x37800000, v51
	v_cndmask_b32_e32 v51, v51, v52, vcc
	v_cmp_class_f32_e32 vcc, v50, v159
	s_nop 1
	v_cndmask_b32_e32 v52, v51, v50, vcc
	v_div_scale_f32 v53, s[0:1], v52, v52, 1.0
	v_rcp_f32_e32 v54, v53
	v_add_co_u32_e32 v50, vcc, s77, v146
	v_fma_f32 v56, -v53, v54, 1.0
	s_nop 0
	v_addc_co_u32_e32 v51, vcc, 0, v147, vcc
	v_div_scale_f32 v55, vcc, 1.0, v52, 1.0
	v_fmac_f32_e32 v54, v56, v54
	v_mul_f32_e32 v56, v55, v54
	v_fma_f32 v57, -v53, v56, v55
	v_fmac_f32_e32 v56, v57, v54
	v_fma_f32 v53, -v53, v56, v55
	v_div_fmas_f32 v53, v53, v54, v56
	v_div_fixup_f32 v52, v53, v52, 1.0
	v_pk_mul_f32 v[46:47], v[46:47], v[52:53] op_sel_hi:[1,0]
	v_pk_mul_f32 v[44:45], v[44:45], v[52:53] op_sel_hi:[1,0]
	v_pk_mul_f32 v[42:43], v[42:43], v[52:53] op_sel_hi:[1,0]
	v_pk_mul_f32 v[40:41], v[40:41], v[52:53] op_sel_hi:[1,0]
	v_pk_mul_f32 v[34:35], v[34:35], v[52:53] op_sel_hi:[1,0]
	v_pk_mul_f32 v[32:33], v[32:33], v[52:53] op_sel_hi:[1,0]
	v_pk_mul_f32 v[38:39], v[38:39], v[52:53] op_sel_hi:[1,0]
	v_pk_mul_f32 v[36:37], v[36:37], v[52:53] op_sel_hi:[1,0]
	v_max_f32_e32 v44, 0, v44
	v_max_f32_e32 v40, 0, v40
	v_max_f32_e32 v45, 0, v45
	v_max_f32_e32 v41, 0, v41
	v_max_f32_e32 v46, 0, v46
	v_max_f32_e32 v42, 0, v42
	v_max_f32_e32 v47, 0, v47
	v_max_f32_e32 v43, 0, v43
	v_max_f32_e32 v32, 0, v32
	v_max_f32_e32 v33, 0, v33
	v_max_f32_e32 v34, 0, v34
	v_max_f32_e32 v35, 0, v35
	v_max_f32_e32 v36, 0, v36
	v_max_f32_e32 v37, 0, v37
	v_max_f32_e32 v38, 0, v38
	v_max_f32_e32 v39, 0, v39
	v_mul_f32_e32 v44, v44, v44
	v_mul_f32_e32 v40, v40, v40
	v_mul_f32_e32 v45, v45, v45
	v_mul_f32_e32 v41, v41, v41
	v_mul_f32_e32 v46, v46, v46
	v_mul_f32_e32 v42, v42, v42
	v_mul_f32_e32 v47, v47, v47
	v_mul_f32_e32 v43, v43, v43
	v_mul_f32_e32 v52, v32, v32
	v_mul_f32_e32 v53, v33, v33
	v_mul_f32_e32 v54, v34, v34
	v_mul_f32_e32 v55, v35, v35
	v_cvt_pk_bf16_f32 v32, v44, v45
	v_cvt_pk_bf16_f32 v33, v46, v47
	v_cvt_pk_bf16_f32 v34, v40, v41
	v_cvt_pk_bf16_f32 v35, v42, v43
	v_mul_f32_e32 v36, v36, v36
	v_mul_f32_e32 v37, v37, v37
	v_mul_f32_e32 v38, v38, v38
	v_mul_f32_e32 v39, v39, v39
	global_store_dwordx4 v[50:51], v[32:35], off
	s_nop 1
	v_cvt_pk_bf16_f32 v32, v36, v37
	v_cvt_pk_bf16_f32 v33, v38, v39
	v_cvt_pk_bf16_f32 v34, v52, v53
	v_cvt_pk_bf16_f32 v35, v54, v55
	global_store_dwordx4 v[48:49], v[32:35], off offset:256
	s_nop 0
	s_waitcnt vmcnt(13)
	v_fmamk_f32 v32, v233, 0x3a000000, v158
	v_mul_f32_e32 v33, 0x4f800000, v32
	v_cmp_gt_f32_e32 vcc, s75, v32
	s_nop 1
	v_cndmask_b32_e32 v34, v32, v33, vcc
	v_sqrt_f32_e32 v35, v34
	v_lshl_add_u64 v[32:33], v[146:147], 0, s[44:45]
	v_add_u32_e32 v36, -1, v35
	v_add_u32_e32 v37, 1, v35
	v_fma_f32 v38, -v36, v35, v34
	v_fma_f32 v39, -v37, v35, v34
	v_cmp_ge_f32_e64 s[4:5], 0, v38
	s_nop 1
	v_cndmask_b32_e64 v35, v35, v36, s[4:5]
	v_cmp_lt_f32_e64 s[4:5], 0, v39
	s_nop 1
	v_cndmask_b32_e64 v35, v35, v37, s[4:5]
	v_mul_f32_e32 v36, 0x37800000, v35
	v_cndmask_b32_e32 v35, v35, v36, vcc
	v_cmp_class_f32_e32 vcc, v34, v159
	s_nop 1
	v_cndmask_b32_e32 v36, v35, v34, vcc
	v_div_scale_f32 v37, s[0:1], v36, v36, 1.0
	v_rcp_f32_e32 v38, v37
	v_add_co_u32_e32 v34, vcc, s78, v146
	v_fma_f32 v40, -v37, v38, 1.0
	s_nop 0
	v_addc_co_u32_e32 v35, vcc, 0, v147, vcc
	v_div_scale_f32 v39, vcc, 1.0, v36, 1.0
	v_fmac_f32_e32 v38, v40, v38
	v_mul_f32_e32 v40, v39, v38
	v_fma_f32 v41, -v37, v40, v39
	v_fmac_f32_e32 v40, v41, v38
	v_fma_f32 v37, -v37, v40, v39
	v_div_fmas_f32 v37, v37, v38, v40
	v_div_fixup_f32 v36, v37, v36, 1.0
	v_pk_mul_f32 v[30:31], v[30:31], v[36:37] op_sel_hi:[1,0]
	v_pk_mul_f32 v[28:29], v[28:29], v[36:37] op_sel_hi:[1,0]
	v_pk_mul_f32 v[26:27], v[26:27], v[36:37] op_sel_hi:[1,0]
	v_pk_mul_f32 v[24:25], v[24:25], v[36:37] op_sel_hi:[1,0]
	v_pk_mul_f32 v[18:19], v[18:19], v[36:37] op_sel_hi:[1,0]
	v_pk_mul_f32 v[16:17], v[16:17], v[36:37] op_sel_hi:[1,0]
	v_pk_mul_f32 v[22:23], v[22:23], v[36:37] op_sel_hi:[1,0]
	v_pk_mul_f32 v[20:21], v[20:21], v[36:37] op_sel_hi:[1,0]
	v_max_f32_e32 v28, 0, v28
	v_max_f32_e32 v24, 0, v24
	v_max_f32_e32 v29, 0, v29
	v_max_f32_e32 v25, 0, v25
	v_max_f32_e32 v30, 0, v30
	v_max_f32_e32 v26, 0, v26
	v_max_f32_e32 v31, 0, v31
	v_max_f32_e32 v27, 0, v27
	v_max_f32_e32 v16, 0, v16
	v_max_f32_e32 v17, 0, v17
	v_max_f32_e32 v18, 0, v18
	v_max_f32_e32 v19, 0, v19
	v_max_f32_e32 v20, 0, v20
	v_max_f32_e32 v21, 0, v21
	v_max_f32_e32 v22, 0, v22
	v_max_f32_e32 v23, 0, v23
	v_mul_f32_e32 v28, v28, v28
	v_mul_f32_e32 v24, v24, v24
	v_mul_f32_e32 v29, v29, v29
	v_mul_f32_e32 v25, v25, v25
	v_mul_f32_e32 v30, v30, v30
	v_mul_f32_e32 v26, v26, v26
	v_mul_f32_e32 v31, v31, v31
	v_mul_f32_e32 v27, v27, v27
	v_mul_f32_e32 v36, v16, v16
	v_mul_f32_e32 v37, v17, v17
	v_mul_f32_e32 v38, v18, v18
	v_mul_f32_e32 v39, v19, v19
	v_cvt_pk_bf16_f32 v16, v28, v29
	v_cvt_pk_bf16_f32 v17, v30, v31
	v_cvt_pk_bf16_f32 v18, v24, v25
	v_cvt_pk_bf16_f32 v19, v26, v27
	v_mul_f32_e32 v20, v20, v20
	v_mul_f32_e32 v21, v21, v21
	v_mul_f32_e32 v22, v22, v22
	v_mul_f32_e32 v23, v23, v23
	global_store_dwordx4 v[34:35], v[16:19], off
	s_nop 1
	v_cvt_pk_bf16_f32 v16, v20, v21
	v_cvt_pk_bf16_f32 v17, v22, v23
	v_cvt_pk_bf16_f32 v18, v36, v37
	v_cvt_pk_bf16_f32 v19, v38, v39
	global_store_dwordx4 v[32:33], v[16:19], off offset:256
	s_nop 0
	s_waitcnt vmcnt(14)
; __device__ __forceinline__ unsigned cvt_pk_bf16(float lo, float hi) { unsigned r; asm volatile("v_cvt_pk_bf16_f32 %0, %1, %2" : "=v"(r) : "v"(lo), "v"(hi)); return r; }
;     __device__ __forceinline__ void operator()(const f32x4 (&acc)[2][2][4][2], const Unit& u, int wr, int wc, int fr, int fq) const {
;     ...
; #pragma unroll
;         for (int ai = 0; ai < 2; ++ai)
; #pragma unroll
;             for (int m = 0; m < 4; ++m) {
;                 const int row = row0 + ai * HALF + m * 16; const float rs = 1.0f / sqrtf(__hip_atomic_load(ss2 + row, __ATOMIC_RELAXED, __HIP_MEMORY_SCOPE_AGENT) * (1.0f / 2048.0f) + EPSN);
;                 bf16_t* rowp = H + (size_t)row * DFF + col0;
; #pragma unroll
;                 for (int bj = 0; bj < 2; ++bj) {
;                     f32x4 v0 = acc[ai][bj][m][0] * rs, v1 = acc[ai][bj][m][1] * rs;
; #pragma unroll
;                     for (int j = 0; j < 4; ++j) { v0[j] = fmaxf(v0[j], 0.f); v0[j] *= v0[j]; v1[j] = fmaxf(v1[j], 0.f); v1[j] *= v1[j]; }
;                     u32x4 w; w.x = cvt_pk_bf16(v0[0], v0[1]); w.y = cvt_pk_bf16(v0[2], v0[3]); w.z = cvt_pk_bf16(v1[0], v1[1]); w.w = cvt_pk_bf16(v1[2], v1[3]);
;                     *(u32x4*)(rowp + bj * HALF) = w;
	v_fmamk_f32 v16, v234, 0x3a000000, v158
	v_mul_f32_e32 v17, 0x4f800000, v16
	v_cmp_gt_f32_e32 vcc, s75, v16
	s_nop 1
	v_cndmask_b32_e32 v18, v16, v17, vcc
	v_sqrt_f32_e32 v19, v18
	v_lshl_add_u64 v[16:17], v[146:147], 0, s[46:47]
	v_add_u32_e32 v20, -1, v19
	v_add_u32_e32 v21, 1, v19
	v_fma_f32 v22, -v20, v19, v18
	v_fma_f32 v23, -v21, v19, v18
	v_cmp_ge_f32_e64 s[4:5], 0, v22
	s_nop 1
	v_cndmask_b32_e64 v19, v19, v20, s[4:5]
	v_cmp_lt_f32_e64 s[4:5], 0, v23
	s_nop 1
	v_cndmask_b32_e64 v19, v19, v21, s[4:5]
	v_mul_f32_e32 v20, 0x37800000, v19
	v_cndmask_b32_e32 v19, v19, v20, vcc
	v_cmp_class_f32_e32 vcc, v18, v159
	s_nop 1
	v_cndmask_b32_e32 v20, v19, v18, vcc
	v_div_scale_f32 v21, s[0:1], v20, v20, 1.0
	v_rcp_f32_e32 v22, v21
	v_add_co_u32_e32 v18, vcc, s79, v146
	v_fma_f32 v24, -v21, v22, 1.0
	s_nop 0
	v_addc_co_u32_e32 v19, vcc, 0, v147, vcc
	v_div_scale_f32 v23, vcc, 1.0, v20, 1.0
	v_fmac_f32_e32 v22, v24, v22
	v_mul_f32_e32 v24, v23, v22
	v_fma_f32 v25, -v21, v24, v23
	v_fmac_f32_e32 v24, v25, v22
	v_fma_f32 v21, -v21, v24, v23
	v_div_fmas_f32 v21, v21, v22, v24
	v_div_fixup_f32 v20, v21, v20, 1.0
	v_pk_mul_f32 v[14:15], v[14:15], v[20:21] op_sel_hi:[1,0]
	v_pk_mul_f32 v[12:13], v[12:13], v[20:21] op_sel_hi:[1,0]
	v_pk_mul_f32 v[10:11], v[10:11], v[20:21] op_sel_hi:[1,0]
	v_pk_mul_f32 v[8:9], v[8:9], v[20:21] op_sel_hi:[1,0]
	v_pk_mul_f32 v[2:3], v[2:3], v[20:21] op_sel_hi:[1,0]
	v_pk_mul_f32 v[0:1], v[0:1], v[20:21] op_sel_hi:[1,0]
	v_pk_mul_f32 v[6:7], v[6:7], v[20:21] op_sel_hi:[1,0]
	v_pk_mul_f32 v[4:5], v[4:5], v[20:21] op_sel_hi:[1,0]
	v_max_f32_e32 v12, 0, v12
	v_max_f32_e32 v8, 0, v8
	v_max_f32_e32 v13, 0, v13
	v_max_f32_e32 v9, 0, v9
	v_max_f32_e32 v14, 0, v14
	v_max_f32_e32 v10, 0, v10
	v_max_f32_e32 v15, 0, v15
	v_max_f32_e32 v11, 0, v11
	v_max_f32_e32 v0, 0, v0
	v_max_f32_e32 v1, 0, v1
	v_max_f32_e32 v2, 0, v2
	v_max_f32_e32 v3, 0, v3
	s_andn2_b64 vcc, exec, s[2:3]
	v_max_f32_e32 v4, 0, v4
	v_max_f32_e32 v5, 0, v5
	v_max_f32_e32 v6, 0, v6
	v_max_f32_e32 v7, 0, v7
	v_mul_f32_e32 v12, v12, v12
	v_mul_f32_e32 v8, v8, v8
	v_mul_f32_e32 v13, v13, v13
	v_mul_f32_e32 v9, v9, v9
	v_mul_f32_e32 v14, v14, v14
	v_mul_f32_e32 v10, v10, v10
	v_mul_f32_e32 v15, v15, v15
	v_mul_f32_e32 v11, v11, v11
	v_mul_f32_e32 v20, v0, v0
	v_mul_f32_e32 v21, v1, v1
	v_mul_f32_e32 v22, v2, v2
	v_mul_f32_e32 v23, v3, v3
	v_cvt_pk_bf16_f32 v0, v12, v13
	v_cvt_pk_bf16_f32 v1, v14, v15
	v_cvt_pk_bf16_f32 v2, v8, v9
	v_cvt_pk_bf16_f32 v3, v10, v11
	s_mov_b64 s[2:3], -1
	v_mul_f32_e32 v4, v4, v4
	v_mul_f32_e32 v5, v5, v5
	v_mul_f32_e32 v6, v6, v6
	v_mul_f32_e32 v7, v7, v7
	global_store_dwordx4 v[18:19], v[0:3], off
	s_nop 1
	v_cvt_pk_bf16_f32 v0, v4, v5
	v_cvt_pk_bf16_f32 v1, v6, v7
	v_cvt_pk_bf16_f32 v2, v20, v21
	v_cvt_pk_bf16_f32 v3, v22, v23
	global_store_dwordx4 v[16:17], v[0:3], off offset:256
	s_cbranch_vccnz .LBB0_853
	s_andn2_b64 vcc, exec, s[20:21]
	s_cbranch_vccnz .LBB0_852
	s_barrier
	s_branch .LBB0_852

; __device__ __forceinline__ unsigned cvt_pk_bf16(float lo, float hi) { unsigned r; asm volatile("v_cvt_pk_bf16_f32 %0, %1, %2" : "=v"(r) : "v"(lo), "v"(hi)); return r; }
;     __device__ __forceinline__ void operator()(const f32x4 (&acc)[2][2][4][2], const Unit& u, int wr, int wc, int fr, int fq) const {
;     ...
; #pragma unroll
;         for (int ai = 0; ai < 2; ++ai)
; #pragma unroll
;             for (int m = 0; m < 4; ++m) {
;                 const int row = row0 + ai * HALF + m * 16; const float rs = 1.0f / sqrtf(__hip_atomic_load(ss2 + row, __ATOMIC_RELAXED, __HIP_MEMORY_SCOPE_AGENT) * (1.0f / 2048.0f) + EPSN);
;                 bf16_t* rowp = H + (size_t)row * DFF + col0;
; #pragma unroll
;                 for (int bj = 0; bj < 2; ++bj) {
;                     f32x4 v0 = acc[ai][bj][m][0] * rs, v1 = acc[ai][bj][m][1] * rs;
; #pragma unroll
;                     for (int j = 0; j < 4; ++j) { v0[j] = fmaxf(v0[j], 0.f); v0[j] *= v0[j]; v1[j] = fmaxf(v1[j], 0.f); v1[j] *= v1[j]; }
;                     u32x4 w; w.x = cvt_pk_bf16(v0[0], v0[1]); w.y = cvt_pk_bf16(v0[2], v0[3]); w.z = cvt_pk_bf16(v1[0], v1[1]); w.w = cvt_pk_bf16(v1[2], v1[3]);
;                     *(u32x4*)(rowp + bj * HALF) = w;
.LBB0_1064:
	v_lshl_add_u32 v150, s6, 8, v152
	v_ashrrev_i32_e32 v151, 31, v150
	v_lshl_add_u64 v[144:145], v[150:151], 2, s[24:25]
	global_load_dword v161, v[144:145], off sc1
	global_load_dword v228, v[144:145], off offset:64 sc1
	global_load_dword v229, v[144:145], off offset:128 sc1
	global_load_dword v230, v[144:145], off offset:192 sc1
	global_load_dword v231, v[144:145], off offset:512 sc1
	global_load_dword v232, v[144:145], off offset:576 sc1
	global_load_dword v233, v[144:145], off offset:640 sc1
	global_load_dword v234, v[144:145], off offset:704 sc1
	v_lshl_or_b32 v146, s0, 8, v154
	v_ashrrev_i32_e32 v147, 31, v146
	v_lshlrev_b64 v[148:149], 1, v[146:147]
	v_lshlrev_b64 v[164:165], 14, v[150:151]
	v_or_b32_e32 v162, 16, v150
	v_ashrrev_i32_e32 v163, 31, v162
	s_waitcnt vmcnt(7)
	v_fmamk_f32 v146, v161, 0x3a000000, v158
	v_mul_f32_e32 v147, 0x4f800000, v146
	v_cmp_gt_f32_e32 vcc, s77, v146
	s_nop 1
	v_cndmask_b32_e32 v151, v146, v147, vcc
	v_sqrt_f32_e32 v161, v151
	v_lshl_add_u64 v[146:147], s[10:11], 0, v[164:165]
	v_lshl_add_u64 v[146:147], v[146:147], 0, v[148:149]
	v_lshl_add_u64 v[164:165], v[162:163], 2, s[24:25]
	v_add_u32_e32 v166, -1, v161
	v_add_u32_e32 v167, 1, v161
	v_fma_f32 v168, -v166, v161, v151
	v_fma_f32 v169, -v167, v161, v151
	v_cmp_ge_f32_e64 s[6:7], 0, v168
	s_nop 1
	v_cndmask_b32_e64 v161, v161, v166, s[6:7]
	v_cmp_lt_f32_e64 s[6:7], 0, v169
	s_nop 1
	v_cndmask_b32_e64 v161, v161, v167, s[6:7]
	v_mul_f32_e32 v166, 0x37800000, v161
	v_cndmask_b32_e32 v161, v161, v166, vcc
	v_cmp_class_f32_e32 vcc, v151, v159
	s_nop 1
	v_cndmask_b32_e32 v151, v161, v151, vcc
	v_div_scale_f32 v161, s[0:1], v151, v151, 1.0
	v_rcp_f32_e32 v166, v161
	v_div_scale_f32 v167, vcc, 1.0, v151, 1.0
	v_fma_f32 v168, -v161, v166, 1.0
	v_fmac_f32_e32 v166, v168, v166
	v_mul_f32_e32 v168, v167, v166
	v_fma_f32 v169, -v161, v168, v167
	v_fmac_f32_e32 v168, v169, v166
	v_fma_f32 v161, -v161, v168, v167
	v_div_fmas_f32 v161, v161, v166, v168
	v_div_fixup_f32 v166, v161, v151, 1.0
	v_pk_mul_f32 v[126:127], v[126:127], v[166:167] op_sel_hi:[1,0]
	v_pk_mul_f32 v[124:125], v[124:125], v[166:167] op_sel_hi:[1,0]
	v_pk_mul_f32 v[122:123], v[122:123], v[166:167] op_sel_hi:[1,0]
	v_pk_mul_f32 v[120:121], v[120:121], v[166:167] op_sel_hi:[1,0]
	v_pk_mul_f32 v[114:115], v[114:115], v[166:167] op_sel_hi:[1,0]
	v_pk_mul_f32 v[112:113], v[112:113], v[166:167] op_sel_hi:[1,0]
	v_pk_mul_f32 v[118:119], v[118:119], v[166:167] op_sel_hi:[1,0]
	v_pk_mul_f32 v[116:117], v[116:117], v[166:167] op_sel_hi:[1,0]
	v_max_f32_e32 v124, 0, v124
	v_max_f32_e32 v120, 0, v120
	v_max_f32_e32 v125, 0, v125
	v_max_f32_e32 v121, 0, v121
	v_max_f32_e32 v126, 0, v126
	v_max_f32_e32 v122, 0, v122
	v_max_f32_e32 v127, 0, v127
	v_max_f32_e32 v123, 0, v123
	v_max_f32_e32 v112, 0, v112
	v_max_f32_e32 v113, 0, v113
	v_max_f32_e32 v114, 0, v114
	v_max_f32_e32 v115, 0, v115
	v_max_f32_e32 v116, 0, v116
	v_max_f32_e32 v117, 0, v117
	v_max_f32_e32 v118, 0, v118
	v_max_f32_e32 v119, 0, v119
	v_mul_f32_e32 v124, v124, v124
	v_mul_f32_e32 v120, v120, v120
	v_mul_f32_e32 v125, v125, v125
	v_mul_f32_e32 v121, v121, v121
	v_mul_f32_e32 v126, v126, v126
	v_mul_f32_e32 v122, v122, v122
	v_mul_f32_e32 v127, v127, v127
	v_mul_f32_e32 v123, v123, v123
	v_mul_f32_e32 v151, v112, v112
	v_mul_f32_e32 v161, v113, v113
	v_mul_f32_e32 v166, v114, v114
	v_mul_f32_e32 v167, v115, v115
	v_cvt_pk_bf16_f32 v112, v124, v125
	v_cvt_pk_bf16_f32 v113, v126, v127
	v_cvt_pk_bf16_f32 v114, v120, v121
	v_cvt_pk_bf16_f32 v115, v122, v123
	v_mul_f32_e32 v116, v116, v116
	v_mul_f32_e32 v117, v117, v117
	v_mul_f32_e32 v118, v118, v118
	v_mul_f32_e32 v119, v119, v119
	global_store_dwordx4 v[146:147], v[112:115], off
	s_nop 1
	v_cvt_pk_bf16_f32 v112, v116, v117
	v_cvt_pk_bf16_f32 v113, v118, v119
	v_cvt_pk_bf16_f32 v114, v151, v161
	v_cvt_pk_bf16_f32 v115, v166, v167
	global_store_dwordx4 v[146:147], v[112:115], off offset:256
	s_nop 0
	s_nop 0
	v_or_b32_e32 v112, 32, v150
	v_ashrrev_i32_e32 v113, 31, v112
	v_lshl_add_u64 v[116:117], v[112:113], 2, s[24:25]
	s_waitcnt vmcnt(8)
	v_fmamk_f32 v114, v228, 0x3a000000, v158
	v_mul_f32_e32 v115, 0x4f800000, v114
	v_cmp_gt_f32_e32 vcc, s77, v114
	s_nop 1
	v_cndmask_b32_e32 v118, v114, v115, vcc
	v_sqrt_f32_e32 v119, v118
	v_lshlrev_b64 v[114:115], 14, v[162:163]
	v_lshl_add_u64 v[114:115], s[10:11], 0, v[114:115]
	v_lshl_add_u64 v[114:115], v[114:115], 0, v[148:149]
	v_add_u32_e32 v120, -1, v119
	v_add_u32_e32 v121, 1, v119
	v_fma_f32 v122, -v120, v119, v118
	v_fma_f32 v123, -v121, v119, v118
	v_cmp_ge_f32_e64 s[6:7], 0, v122
	s_nop 1
	v_cndmask_b32_e64 v119, v119, v120, s[6:7]
	v_cmp_lt_f32_e64 s[6:7], 0, v123
	s_nop 1
	v_cndmask_b32_e64 v119, v119, v121, s[6:7]
	v_mul_f32_e32 v120, 0x37800000, v119
	v_cndmask_b32_e32 v119, v119, v120, vcc
	v_cmp_class_f32_e32 vcc, v118, v159
	s_nop 1
	v_cndmask_b32_e32 v118, v119, v118, vcc
	v_div_scale_f32 v119, s[0:1], v118, v118, 1.0
	v_rcp_f32_e32 v120, v119
	v_div_scale_f32 v121, vcc, 1.0, v118, 1.0
	v_fma_f32 v122, -v119, v120, 1.0
	v_fmac_f32_e32 v120, v122, v120
	v_mul_f32_e32 v122, v121, v120
	v_fma_f32 v123, -v119, v122, v121
	v_fmac_f32_e32 v122, v123, v120
	v_fma_f32 v119, -v119, v122, v121
	v_div_fmas_f32 v119, v119, v120, v122
	v_div_fixup_f32 v118, v119, v118, 1.0
	v_pk_mul_f32 v[110:111], v[110:111], v[118:119] op_sel_hi:[1,0]
	v_pk_mul_f32 v[108:109], v[108:109], v[118:119] op_sel_hi:[1,0]
	v_pk_mul_f32 v[106:107], v[106:107], v[118:119] op_sel_hi:[1,0]
	v_pk_mul_f32 v[104:105], v[104:105], v[118:119] op_sel_hi:[1,0]
	v_pk_mul_f32 v[98:99], v[98:99], v[118:119] op_sel_hi:[1,0]
	v_pk_mul_f32 v[96:97], v[96:97], v[118:119] op_sel_hi:[1,0]
; __device__ __forceinline__ unsigned cvt_pk_bf16(float lo, float hi) { unsigned r; asm volatile("v_cvt_pk_bf16_f32 %0, %1, %2" : "=v"(r) : "v"(lo), "v"(hi)); return r; }
;     __device__ __forceinline__ void operator()(const f32x4 (&acc)[2][2][4][2], const Unit& u, int wr, int wc, int fr, int fq) const {
;     ...
; #pragma unroll
;         for (int ai = 0; ai < 2; ++ai)
; #pragma unroll
;             for (int m = 0; m < 4; ++m) {
;                 const int row = row0 + ai * HALF + m * 16; const float rs = 1.0f / sqrtf(__hip_atomic_load(ss2 + row, __ATOMIC_RELAXED, __HIP_MEMORY_SCOPE_AGENT) * (1.0f / 2048.0f) + EPSN);
;                 bf16_t* rowp = H + (size_t)row * DFF + col0;
; #pragma unroll
;                 for (int bj = 0; bj < 2; ++bj) {
;                     f32x4 v0 = acc[ai][bj][m][0] * rs, v1 = acc[ai][bj][m][1] * rs;
; #pragma unroll
;                     for (int j = 0; j < 4; ++j) { v0[j] = fmaxf(v0[j], 0.f); v0[j] *= v0[j]; v1[j] = fmaxf(v1[j], 0.f); v1[j] *= v1[j]; }
;                     u32x4 w; w.x = cvt_pk_bf16(v0[0], v0[1]); w.y = cvt_pk_bf16(v0[2], v0[3]); w.z = cvt_pk_bf16(v1[0], v1[1]); w.w = cvt_pk_bf16(v1[2], v1[3]);
;                     *(u32x4*)(rowp + bj * HALF) = w;
	v_pk_mul_f32 v[102:103], v[102:103], v[118:119] op_sel_hi:[1,0]
	v_pk_mul_f32 v[100:101], v[100:101], v[118:119] op_sel_hi:[1,0]
	v_max_f32_e32 v108, 0, v108
	v_max_f32_e32 v104, 0, v104
	v_max_f32_e32 v109, 0, v109
	v_max_f32_e32 v105, 0, v105
	v_max_f32_e32 v110, 0, v110
	v_max_f32_e32 v106, 0, v106
	v_max_f32_e32 v111, 0, v111
	v_max_f32_e32 v107, 0, v107
	v_max_f32_e32 v96, 0, v96
	v_max_f32_e32 v97, 0, v97
	v_max_f32_e32 v98, 0, v98
	v_max_f32_e32 v99, 0, v99
	v_max_f32_e32 v100, 0, v100
	v_max_f32_e32 v101, 0, v101
	v_max_f32_e32 v102, 0, v102
	v_max_f32_e32 v103, 0, v103
	v_mul_f32_e32 v108, v108, v108
	v_mul_f32_e32 v104, v104, v104
	v_mul_f32_e32 v109, v109, v109
	v_mul_f32_e32 v105, v105, v105
	v_mul_f32_e32 v110, v110, v110
	v_mul_f32_e32 v106, v106, v106
	v_mul_f32_e32 v111, v111, v111
	v_mul_f32_e32 v107, v107, v107
	v_mul_f32_e32 v118, v96, v96
	v_mul_f32_e32 v119, v97, v97
	v_mul_f32_e32 v120, v98, v98
	v_mul_f32_e32 v121, v99, v99
	v_cvt_pk_bf16_f32 v96, v108, v109
	v_cvt_pk_bf16_f32 v97, v110, v111
	v_cvt_pk_bf16_f32 v98, v104, v105
	v_cvt_pk_bf16_f32 v99, v106, v107
	v_mul_f32_e32 v100, v100, v100
	v_mul_f32_e32 v101, v101, v101
	v_mul_f32_e32 v102, v102, v102
	v_mul_f32_e32 v103, v103, v103
	global_store_dwordx4 v[114:115], v[96:99], off
	s_nop 1
	v_cvt_pk_bf16_f32 v96, v100, v101
	v_cvt_pk_bf16_f32 v97, v102, v103
	v_cvt_pk_bf16_f32 v98, v118, v119
	v_cvt_pk_bf16_f32 v99, v120, v121
	global_store_dwordx4 v[114:115], v[96:99], off offset:256
	s_nop 0
	s_nop 0
	v_or_b32_e32 v96, 48, v150
	v_ashrrev_i32_e32 v97, 31, v96
	v_lshl_add_u64 v[100:101], v[96:97], 2, s[24:25]
	s_waitcnt vmcnt(9)
	v_fmamk_f32 v98, v229, 0x3a000000, v158
	v_mul_f32_e32 v99, 0x4f800000, v98
	v_cmp_gt_f32_e32 vcc, s77, v98
	s_nop 1
	v_cndmask_b32_e32 v102, v98, v99, vcc
	v_sqrt_f32_e32 v103, v102
	v_lshlrev_b64 v[98:99], 14, v[112:113]
	v_lshl_add_u64 v[98:99], s[10:11], 0, v[98:99]
	v_lshl_add_u64 v[98:99], v[98:99], 0, v[148:149]
	v_add_u32_e32 v104, -1, v103
	v_add_u32_e32 v105, 1, v103
	v_fma_f32 v106, -v104, v103, v102
	v_fma_f32 v107, -v105, v103, v102
	v_cmp_ge_f32_e64 s[6:7], 0, v106
	s_nop 1
	v_cndmask_b32_e64 v103, v103, v104, s[6:7]
	v_cmp_lt_f32_e64 s[6:7], 0, v107
	s_nop 1
	v_cndmask_b32_e64 v103, v103, v105, s[6:7]
	v_mul_f32_e32 v104, 0x37800000, v103
	v_cndmask_b32_e32 v103, v103, v104, vcc
	v_cmp_class_f32_e32 vcc, v102, v159
	s_nop 1
	v_cndmask_b32_e32 v102, v103, v102, vcc
	v_div_scale_f32 v103, s[0:1], v102, v102, 1.0
	v_rcp_f32_e32 v104, v103
	v_div_scale_f32 v105, vcc, 1.0, v102, 1.0
	v_fma_f32 v106, -v103, v104, 1.0
	v_fmac_f32_e32 v104, v106, v104
	v_mul_f32_e32 v106, v105, v104
	v_fma_f32 v107, -v103, v106, v105
	v_fmac_f32_e32 v106, v107, v104
	v_fma_f32 v103, -v103, v106, v105
	v_div_fmas_f32 v103, v103, v104, v106
	v_div_fixup_f32 v102, v103, v102, 1.0
	v_pk_mul_f32 v[94:95], v[94:95], v[102:103] op_sel_hi:[1,0]
	v_pk_mul_f32 v[92:93], v[92:93], v[102:103] op_sel_hi:[1,0]
	v_pk_mul_f32 v[90:91], v[90:91], v[102:103] op_sel_hi:[1,0]
	v_pk_mul_f32 v[88:89], v[88:89], v[102:103] op_sel_hi:[1,0]
	v_pk_mul_f32 v[82:83], v[82:83], v[102:103] op_sel_hi:[1,0]
	v_pk_mul_f32 v[80:81], v[80:81], v[102:103] op_sel_hi:[1,0]
	v_pk_mul_f32 v[86:87], v[86:87], v[102:103] op_sel_hi:[1,0]
	v_pk_mul_f32 v[84:85], v[84:85], v[102:103] op_sel_hi:[1,0]
	v_max_f32_e32 v92, 0, v92
	v_max_f32_e32 v88, 0, v88
	v_max_f32_e32 v93, 0, v93
	v_max_f32_e32 v89, 0, v89
	v_max_f32_e32 v94, 0, v94
	v_max_f32_e32 v90, 0, v90
	v_max_f32_e32 v95, 0, v95
	v_max_f32_e32 v91, 0, v91
	v_max_f32_e32 v80, 0, v80
	v_max_f32_e32 v81, 0, v81
	v_max_f32_e32 v82, 0, v82
	v_max_f32_e32 v83, 0, v83
	v_max_f32_e32 v84, 0, v84
	v_max_f32_e32 v85, 0, v85
	v_max_f32_e32 v86, 0, v86
	v_max_f32_e32 v87, 0, v87
	v_mul_f32_e32 v92, v92, v92
	v_mul_f32_e32 v88, v88, v88
	v_mul_f32_e32 v93, v93, v93
	v_mul_f32_e32 v89, v89, v89
	v_mul_f32_e32 v94, v94, v94
	v_mul_f32_e32 v90, v90, v90
	v_mul_f32_e32 v95, v95, v95
	v_mul_f32_e32 v91, v91, v91
	v_mul_f32_e32 v102, v80, v80
	v_mul_f32_e32 v103, v81, v81
	v_mul_f32_e32 v104, v82, v82
	v_mul_f32_e32 v105, v83, v83
	v_cvt_pk_bf16_f32 v80, v92, v93
	v_cvt_pk_bf16_f32 v81, v94, v95
	v_cvt_pk_bf16_f32 v82, v88, v89
	v_cvt_pk_bf16_f32 v83, v90, v91
	v_mul_f32_e32 v84, v84, v84
	v_mul_f32_e32 v85, v85, v85
	v_mul_f32_e32 v86, v86, v86
	v_mul_f32_e32 v87, v87, v87
	global_store_dwordx4 v[98:99], v[80:83], off
	s_nop 1
	v_cvt_pk_bf16_f32 v80, v84, v85
	v_cvt_pk_bf16_f32 v81, v86, v87
	v_cvt_pk_bf16_f32 v82, v102, v103
	v_cvt_pk_bf16_f32 v83, v104, v105
	global_store_dwordx4 v[98:99], v[80:83], off offset:256
	s_nop 0
	s_waitcnt vmcnt(10)
; __device__ __forceinline__ unsigned cvt_pk_bf16(float lo, float hi) { unsigned r; asm volatile("v_cvt_pk_bf16_f32 %0, %1, %2" : "=v"(r) : "v"(lo), "v"(hi)); return r; }
;     __device__ __forceinline__ void operator()(const f32x4 (&acc)[2][2][4][2], const Unit& u, int wr, int wc, int fr, int fq) const {
;     ...
; #pragma unroll
;         for (int ai = 0; ai < 2; ++ai)
; #pragma unroll
;             for (int m = 0; m < 4; ++m) {
;                 const int row = row0 + ai * HALF + m * 16; const float rs = 1.0f / sqrtf(__hip_atomic_load(ss2 + row, __ATOMIC_RELAXED, __HIP_MEMORY_SCOPE_AGENT) * (1.0f / 2048.0f) + EPSN);
;                 bf16_t* rowp = H + (size_t)row * DFF + col0;
; #pragma unroll
;                 for (int bj = 0; bj < 2; ++bj) {
;                     f32x4 v0 = acc[ai][bj][m][0] * rs, v1 = acc[ai][bj][m][1] * rs;
; #pragma unroll
;                     for (int j = 0; j < 4; ++j) { v0[j] = fmaxf(v0[j], 0.f); v0[j] *= v0[j]; v1[j] = fmaxf(v1[j], 0.f); v1[j] *= v1[j]; }
;                     u32x4 w; w.x = cvt_pk_bf16(v0[0], v0[1]); w.y = cvt_pk_bf16(v0[2], v0[3]); w.z = cvt_pk_bf16(v1[0], v1[1]); w.w = cvt_pk_bf16(v1[2], v1[3]);
;                     *(u32x4*)(rowp + bj * HALF) = w;
	v_fmamk_f32 v80, v230, 0x3a000000, v158
	v_mul_f32_e32 v81, 0x4f800000, v80
	v_cmp_gt_f32_e32 vcc, s77, v80
	s_nop 1
	v_cndmask_b32_e32 v82, v80, v81, vcc
	v_sqrt_f32_e32 v83, v82
	v_lshlrev_b64 v[80:81], 14, v[96:97]
	v_lshl_add_u64 v[80:81], s[10:11], 0, v[80:81]
	v_lshl_add_u64 v[80:81], v[80:81], 0, v[148:149]
	v_add_u32_e32 v84, -1, v83
	v_add_u32_e32 v85, 1, v83
	v_fma_f32 v86, -v84, v83, v82
	v_fma_f32 v87, -v85, v83, v82
	v_cmp_ge_f32_e64 s[6:7], 0, v86
	s_nop 1
	v_cndmask_b32_e64 v83, v83, v84, s[6:7]
	v_cmp_lt_f32_e64 s[6:7], 0, v87
	s_nop 1
	v_cndmask_b32_e64 v83, v83, v85, s[6:7]
	v_mul_f32_e32 v84, 0x37800000, v83
	v_cndmask_b32_e32 v83, v83, v84, vcc
	v_cmp_class_f32_e32 vcc, v82, v159
	s_nop 1
	v_cndmask_b32_e32 v82, v83, v82, vcc
	v_div_scale_f32 v83, s[0:1], v82, v82, 1.0
	v_rcp_f32_e32 v84, v83
	v_div_scale_f32 v85, vcc, 1.0, v82, 1.0
	v_fma_f32 v86, -v83, v84, 1.0
	v_fmac_f32_e32 v84, v86, v84
	v_mul_f32_e32 v86, v85, v84
	v_fma_f32 v87, -v83, v86, v85
	v_fmac_f32_e32 v86, v87, v84
	v_fma_f32 v83, -v83, v86, v85
	v_div_fmas_f32 v83, v83, v84, v86
	v_div_fixup_f32 v82, v83, v82, 1.0
	v_pk_mul_f32 v[78:79], v[78:79], v[82:83] op_sel_hi:[1,0]
	v_pk_mul_f32 v[76:77], v[76:77], v[82:83] op_sel_hi:[1,0]
	v_pk_mul_f32 v[74:75], v[74:75], v[82:83] op_sel_hi:[1,0]
	v_pk_mul_f32 v[72:73], v[72:73], v[82:83] op_sel_hi:[1,0]
	v_pk_mul_f32 v[66:67], v[66:67], v[82:83] op_sel_hi:[1,0]
	v_pk_mul_f32 v[64:65], v[64:65], v[82:83] op_sel_hi:[1,0]
	v_pk_mul_f32 v[70:71], v[70:71], v[82:83] op_sel_hi:[1,0]
	v_pk_mul_f32 v[68:69], v[68:69], v[82:83] op_sel_hi:[1,0]
	v_max_f32_e32 v76, 0, v76
	v_max_f32_e32 v72, 0, v72
	v_max_f32_e32 v77, 0, v77
	v_max_f32_e32 v73, 0, v73
	v_max_f32_e32 v78, 0, v78
	v_max_f32_e32 v74, 0, v74
	v_max_f32_e32 v79, 0, v79
	v_max_f32_e32 v75, 0, v75
	v_max_f32_e32 v64, 0, v64
	v_max_f32_e32 v65, 0, v65
	v_max_f32_e32 v66, 0, v66
	v_max_f32_e32 v67, 0, v67
	v_max_f32_e32 v68, 0, v68
	v_max_f32_e32 v69, 0, v69
	v_max_f32_e32 v70, 0, v70
	v_max_f32_e32 v71, 0, v71
	v_mul_f32_e32 v76, v76, v76
	v_mul_f32_e32 v72, v72, v72
	v_mul_f32_e32 v77, v77, v77
	v_mul_f32_e32 v73, v73, v73
	v_mul_f32_e32 v78, v78, v78
	v_mul_f32_e32 v74, v74, v74
	v_mul_f32_e32 v79, v79, v79
	v_mul_f32_e32 v75, v75, v75
	v_mul_f32_e32 v82, v64, v64
	v_mul_f32_e32 v83, v65, v65
	v_mul_f32_e32 v84, v66, v66
	v_mul_f32_e32 v85, v67, v67
	v_cvt_pk_bf16_f32 v64, v76, v77
	v_cvt_pk_bf16_f32 v65, v78, v79
	v_cvt_pk_bf16_f32 v66, v72, v73
	v_cvt_pk_bf16_f32 v67, v74, v75
	v_mul_f32_e32 v68, v68, v68
	v_mul_f32_e32 v69, v69, v69
	v_mul_f32_e32 v70, v70, v70
	v_mul_f32_e32 v71, v71, v71
	global_store_dwordx4 v[80:81], v[64:67], off
	s_nop 1
	v_cvt_pk_bf16_f32 v64, v68, v69
	v_cvt_pk_bf16_f32 v65, v70, v71
	v_cvt_pk_bf16_f32 v66, v82, v83
	v_cvt_pk_bf16_f32 v67, v84, v85
	global_store_dwordx4 v[80:81], v[64:67], off offset:256
	s_nop 0
	s_waitcnt vmcnt(11)
	v_fmamk_f32 v64, v231, 0x3a000000, v158
	v_mul_f32_e32 v65, 0x4f800000, v64
	v_cmp_gt_f32_e32 vcc, s77, v64
	s_nop 1
	v_cndmask_b32_e32 v66, v64, v65, vcc
	v_sqrt_f32_e32 v67, v66
	v_lshl_add_u64 v[64:65], v[146:147], 0, s[40:41]
	v_add_u32_e32 v68, -1, v67
	v_add_u32_e32 v69, 1, v67
	v_fma_f32 v70, -v68, v67, v66
	v_fma_f32 v71, -v69, v67, v66
	v_cmp_ge_f32_e64 s[6:7], 0, v70
	s_nop 1
	v_cndmask_b32_e64 v67, v67, v68, s[6:7]
	v_cmp_lt_f32_e64 s[6:7], 0, v71
	s_nop 1
	v_cndmask_b32_e64 v67, v67, v69, s[6:7]
	v_mul_f32_e32 v68, 0x37800000, v67
	v_cndmask_b32_e32 v67, v67, v68, vcc
	v_cmp_class_f32_e32 vcc, v66, v159
	s_nop 1
	v_cndmask_b32_e32 v68, v67, v66, vcc
	v_div_scale_f32 v69, s[0:1], v68, v68, 1.0
	v_rcp_f32_e32 v70, v69
	v_add_co_u32_e32 v66, vcc, s78, v146
	v_fma_f32 v72, -v69, v70, 1.0
	s_nop 0
	v_addc_co_u32_e32 v67, vcc, 0, v147, vcc
	v_div_scale_f32 v71, vcc, 1.0, v68, 1.0
	v_fmac_f32_e32 v70, v72, v70
	v_mul_f32_e32 v72, v71, v70
	v_fma_f32 v73, -v69, v72, v71
	v_fmac_f32_e32 v72, v73, v70
	v_fma_f32 v69, -v69, v72, v71
	v_div_fmas_f32 v69, v69, v70, v72
	v_div_fixup_f32 v68, v69, v68, 1.0
	v_pk_mul_f32 v[62:63], v[62:63], v[68:69] op_sel_hi:[1,0]
	v_pk_mul_f32 v[60:61], v[60:61], v[68:69] op_sel_hi:[1,0]
	v_pk_mul_f32 v[58:59], v[58:59], v[68:69] op_sel_hi:[1,0]
	v_pk_mul_f32 v[56:57], v[56:57], v[68:69] op_sel_hi:[1,0]
	v_pk_mul_f32 v[50:51], v[50:51], v[68:69] op_sel_hi:[1,0]
	v_pk_mul_f32 v[48:49], v[48:49], v[68:69] op_sel_hi:[1,0]
	v_pk_mul_f32 v[54:55], v[54:55], v[68:69] op_sel_hi:[1,0]
	v_pk_mul_f32 v[52:53], v[52:53], v[68:69] op_sel_hi:[1,0]
	v_max_f32_e32 v60, 0, v60
	v_max_f32_e32 v56, 0, v56
	v_max_f32_e32 v61, 0, v61
	v_max_f32_e32 v57, 0, v57
	v_max_f32_e32 v62, 0, v62
	v_max_f32_e32 v58, 0, v58
	v_max_f32_e32 v63, 0, v63
	v_max_f32_e32 v59, 0, v59
	v_max_f32_e32 v48, 0, v48
	v_max_f32_e32 v49, 0, v49
	v_max_f32_e32 v50, 0, v50
	v_max_f32_e32 v51, 0, v51
	v_max_f32_e32 v52, 0, v52
	v_max_f32_e32 v53, 0, v53
	v_max_f32_e32 v54, 0, v54
	v_max_f32_e32 v55, 0, v55
	v_mul_f32_e32 v60, v60, v60
	v_mul_f32_e32 v56, v56, v56
	v_mul_f32_e32 v61, v61, v61
	v_mul_f32_e32 v57, v57, v57
	v_mul_f32_e32 v62, v62, v62
	v_mul_f32_e32 v58, v58, v58
	v_mul_f32_e32 v63, v63, v63
	v_mul_f32_e32 v59, v59, v59
	v_mul_f32_e32 v68, v48, v48
	v_mul_f32_e32 v69, v49, v49
	v_mul_f32_e32 v70, v50, v50
	v_mul_f32_e32 v71, v51, v51
	v_cvt_pk_bf16_f32 v48, v60, v61
	v_cvt_pk_bf16_f32 v49, v62, v63
	v_cvt_pk_bf16_f32 v50, v56, v57
	v_cvt_pk_bf16_f32 v51, v58, v59
	v_mul_f32_e32 v52, v52, v52
	v_mul_f32_e32 v53, v53, v53
	v_mul_f32_e32 v54, v54, v54
	v_mul_f32_e32 v55, v55, v55
	global_store_dwordx4 v[66:67], v[48:51], off
	s_nop 1
	v_cvt_pk_bf16_f32 v48, v52, v53
	v_cvt_pk_bf16_f32 v49, v54, v55
	v_cvt_pk_bf16_f32 v50, v68, v69
	v_cvt_pk_bf16_f32 v51, v70, v71
	global_store_dwordx4 v[64:65], v[48:51], off offset:256
	s_nop 0
	s_waitcnt vmcnt(12)
; __device__ __forceinline__ unsigned cvt_pk_bf16(float lo, float hi) { unsigned r; asm volatile("v_cvt_pk_bf16_f32 %0, %1, %2" : "=v"(r) : "v"(lo), "v"(hi)); return r; }
;     __device__ __forceinline__ void operator()(const f32x4 (&acc)[2][2][4][2], const Unit& u, int wr, int wc, int fr, int fq) const {
;     ...
; #pragma unroll
;         for (int ai = 0; ai < 2; ++ai)
; #pragma unroll
;             for (int m = 0; m < 4; ++m) {
;                 const int row = row0 + ai * HALF + m * 16; const float rs = 1.0f / sqrtf(__hip_atomic_load(ss2 + row, __ATOMIC_RELAXED, __HIP_MEMORY_SCOPE_AGENT) * (1.0f / 2048.0f) + EPSN);
;                 bf16_t* rowp = H + (size_t)row * DFF + col0;
; #pragma unroll
;                 for (int bj = 0; bj < 2; ++bj) {
;                     f32x4 v0 = acc[ai][bj][m][0] * rs, v1 = acc[ai][bj][m][1] * rs;
; #pragma unroll
;                     for (int j = 0; j < 4; ++j) { v0[j] = fmaxf(v0[j], 0.f); v0[j] *= v0[j]; v1[j] = fmaxf(v1[j], 0.f); v1[j] *= v1[j]; }
;                     u32x4 w; w.x = cvt_pk_bf16(v0[0], v0[1]); w.y = cvt_pk_bf16(v0[2], v0[3]); w.z = cvt_pk_bf16(v1[0], v1[1]); w.w = cvt_pk_bf16(v1[2], v1[3]);
;                     *(u32x4*)(rowp + bj * HALF) = w;
	v_fmamk_f32 v48, v232, 0x3a000000, v158
	v_mul_f32_e32 v49, 0x4f800000, v48
	v_cmp_gt_f32_e32 vcc, s77, v48
	s_nop 1
	v_cndmask_b32_e32 v50, v48, v49, vcc
	v_sqrt_f32_e32 v51, v50
	v_lshl_add_u64 v[48:49], v[146:147], 0, s[42:43]
	v_add_u32_e32 v52, -1, v51
	v_add_u32_e32 v53, 1, v51
	v_fma_f32 v54, -v52, v51, v50
	v_fma_f32 v55, -v53, v51, v50
	v_cmp_ge_f32_e64 s[6:7], 0, v54
	s_nop 1
	v_cndmask_b32_e64 v51, v51, v52, s[6:7]
	v_cmp_lt_f32_e64 s[6:7], 0, v55
	s_nop 1
	v_cndmask_b32_e64 v51, v51, v53, s[6:7]
	v_mul_f32_e32 v52, 0x37800000, v51
	v_cndmask_b32_e32 v51, v51, v52, vcc
	v_cmp_class_f32_e32 vcc, v50, v159
	s_nop 1
	v_cndmask_b32_e32 v52, v51, v50, vcc
	v_div_scale_f32 v53, s[0:1], v52, v52, 1.0
	v_rcp_f32_e32 v54, v53
	v_add_co_u32_e32 v50, vcc, s79, v146
	v_fma_f32 v56, -v53, v54, 1.0
	s_nop 0
	v_addc_co_u32_e32 v51, vcc, 0, v147, vcc
	v_div_scale_f32 v55, vcc, 1.0, v52, 1.0
	v_fmac_f32_e32 v54, v56, v54
	v_mul_f32_e32 v56, v55, v54
	v_fma_f32 v57, -v53, v56, v55
	v_fmac_f32_e32 v56, v57, v54
	v_fma_f32 v53, -v53, v56, v55
	v_div_fmas_f32 v53, v53, v54, v56
	v_div_fixup_f32 v52, v53, v52, 1.0
	v_pk_mul_f32 v[46:47], v[46:47], v[52:53] op_sel_hi:[1,0]
	v_pk_mul_f32 v[44:45], v[44:45], v[52:53] op_sel_hi:[1,0]
	v_pk_mul_f32 v[42:43], v[42:43], v[52:53] op_sel_hi:[1,0]
	v_pk_mul_f32 v[40:41], v[40:41], v[52:53] op_sel_hi:[1,0]
	v_pk_mul_f32 v[34:35], v[34:35], v[52:53] op_sel_hi:[1,0]
	v_pk_mul_f32 v[32:33], v[32:33], v[52:53] op_sel_hi:[1,0]
	v_pk_mul_f32 v[38:39], v[38:39], v[52:53] op_sel_hi:[1,0]
	v_pk_mul_f32 v[36:37], v[36:37], v[52:53] op_sel_hi:[1,0]
	v_max_f32_e32 v44, 0, v44
	v_max_f32_e32 v40, 0, v40
	v_max_f32_e32 v45, 0, v45
	v_max_f32_e32 v41, 0, v41
	v_max_f32_e32 v46, 0, v46
	v_max_f32_e32 v42, 0, v42
	v_max_f32_e32 v47, 0, v47
	v_max_f32_e32 v43, 0, v43
	v_max_f32_e32 v32, 0, v32
	v_max_f32_e32 v33, 0, v33
	v_max_f32_e32 v34, 0, v34
	v_max_f32_e32 v35, 0, v35
	v_max_f32_e32 v36, 0, v36
	v_max_f32_e32 v37, 0, v37
	v_max_f32_e32 v38, 0, v38
	v_max_f32_e32 v39, 0, v39
	v_mul_f32_e32 v44, v44, v44
	v_mul_f32_e32 v40, v40, v40
	v_mul_f32_e32 v45, v45, v45
	v_mul_f32_e32 v41, v41, v41
	v_mul_f32_e32 v46, v46, v46
	v_mul_f32_e32 v42, v42, v42
	v_mul_f32_e32 v47, v47, v47
	v_mul_f32_e32 v43, v43, v43
	v_mul_f32_e32 v52, v32, v32
	v_mul_f32_e32 v53, v33, v33
	v_mul_f32_e32 v54, v34, v34
	v_mul_f32_e32 v55, v35, v35
	v_cvt_pk_bf16_f32 v32, v44, v45
	v_cvt_pk_bf16_f32 v33, v46, v47
	v_cvt_pk_bf16_f32 v34, v40, v41
	v_cvt_pk_bf16_f32 v35, v42, v43
	v_mul_f32_e32 v36, v36, v36
	v_mul_f32_e32 v37, v37, v37
	v_mul_f32_e32 v38, v38, v38
	v_mul_f32_e32 v39, v39, v39
	global_store_dwordx4 v[50:51], v[32:35], off
	s_nop 1
	v_cvt_pk_bf16_f32 v32, v36, v37
	v_cvt_pk_bf16_f32 v33, v38, v39
	v_cvt_pk_bf16_f32 v34, v52, v53
	v_cvt_pk_bf16_f32 v35, v54, v55
	global_store_dwordx4 v[48:49], v[32:35], off offset:256
	s_nop 0
	s_waitcnt vmcnt(13)
	v_fmamk_f32 v32, v233, 0x3a000000, v158
	v_mul_f32_e32 v33, 0x4f800000, v32
	v_cmp_gt_f32_e32 vcc, s77, v32
	s_nop 1
	v_cndmask_b32_e32 v34, v32, v33, vcc
	v_sqrt_f32_e32 v35, v34
	v_lshl_add_u64 v[32:33], v[146:147], 0, s[44:45]
	v_add_u32_e32 v36, -1, v35
	v_add_u32_e32 v37, 1, v35
	v_fma_f32 v38, -v36, v35, v34
	v_fma_f32 v39, -v37, v35, v34
	v_cmp_ge_f32_e64 s[6:7], 0, v38
	s_nop 1
	v_cndmask_b32_e64 v35, v35, v36, s[6:7]
	v_cmp_lt_f32_e64 s[6:7], 0, v39
	s_nop 1
	v_cndmask_b32_e64 v35, v35, v37, s[6:7]
	v_mul_f32_e32 v36, 0x37800000, v35
	v_cndmask_b32_e32 v35, v35, v36, vcc
	v_cmp_class_f32_e32 vcc, v34, v159
	s_nop 1
	v_cndmask_b32_e32 v36, v35, v34, vcc
	v_div_scale_f32 v37, s[0:1], v36, v36, 1.0
	v_rcp_f32_e32 v38, v37
	v_add_co_u32_e32 v34, vcc, s80, v146
	v_fma_f32 v40, -v37, v38, 1.0
	s_nop 0
	v_addc_co_u32_e32 v35, vcc, 0, v147, vcc
	v_div_scale_f32 v39, vcc, 1.0, v36, 1.0
	v_fmac_f32_e32 v38, v40, v38
	v_mul_f32_e32 v40, v39, v38
	v_fma_f32 v41, -v37, v40, v39
	v_fmac_f32_e32 v40, v41, v38
	v_fma_f32 v37, -v37, v40, v39
	v_div_fmas_f32 v37, v37, v38, v40
	v_div_fixup_f32 v36, v37, v36, 1.0
	v_pk_mul_f32 v[30:31], v[30:31], v[36:37] op_sel_hi:[1,0]
	v_pk_mul_f32 v[28:29], v[28:29], v[36:37] op_sel_hi:[1,0]
	v_pk_mul_f32 v[26:27], v[26:27], v[36:37] op_sel_hi:[1,0]
	v_pk_mul_f32 v[24:25], v[24:25], v[36:37] op_sel_hi:[1,0]
	v_pk_mul_f32 v[18:19], v[18:19], v[36:37] op_sel_hi:[1,0]
	v_pk_mul_f32 v[16:17], v[16:17], v[36:37] op_sel_hi:[1,0]
	v_pk_mul_f32 v[22:23], v[22:23], v[36:37] op_sel_hi:[1,0]
	v_pk_mul_f32 v[20:21], v[20:21], v[36:37] op_sel_hi:[1,0]
	v_max_f32_e32 v28, 0, v28
	v_max_f32_e32 v24, 0, v24
	v_max_f32_e32 v29, 0, v29
	v_max_f32_e32 v25, 0, v25
	v_max_f32_e32 v30, 0, v30
	v_max_f32_e32 v26, 0, v26
	v_max_f32_e32 v31, 0, v31
	v_max_f32_e32 v27, 0, v27
	v_max_f32_e32 v16, 0, v16
	v_max_f32_e32 v17, 0, v17
	v_max_f32_e32 v18, 0, v18
	v_max_f32_e32 v19, 0, v19
	v_max_f32_e32 v20, 0, v20
	v_max_f32_e32 v21, 0, v21
	v_max_f32_e32 v22, 0, v22
	v_max_f32_e32 v23, 0, v23
	v_mul_f32_e32 v28, v28, v28
	v_mul_f32_e32 v24, v24, v24
	v_mul_f32_e32 v29, v29, v29
	v_mul_f32_e32 v25, v25, v25
	v_mul_f32_e32 v30, v30, v30
	v_mul_f32_e32 v26, v26, v26
	v_mul_f32_e32 v31, v31, v31
	v_mul_f32_e32 v27, v27, v27
	v_mul_f32_e32 v36, v16, v16
	v_mul_f32_e32 v37, v17, v17
	v_mul_f32_e32 v38, v18, v18
	v_mul_f32_e32 v39, v19, v19
	v_cvt_pk_bf16_f32 v16, v28, v29
	v_cvt_pk_bf16_f32 v17, v30, v31
	v_cvt_pk_bf16_f32 v18, v24, v25
	v_cvt_pk_bf16_f32 v19, v26, v27
	v_mul_f32_e32 v20, v20, v20
	v_mul_f32_e32 v21, v21, v21
	v_mul_f32_e32 v22, v22, v22
	v_mul_f32_e32 v23, v23, v23
	global_store_dwordx4 v[34:35], v[16:19], off
	s_nop 1
	v_cvt_pk_bf16_f32 v16, v20, v21
	v_cvt_pk_bf16_f32 v17, v22, v23
	v_cvt_pk_bf16_f32 v18, v36, v37
	v_cvt_pk_bf16_f32 v19, v38, v39
	global_store_dwordx4 v[32:33], v[16:19], off offset:256
	s_nop 0
	s_waitcnt vmcnt(14)
; __device__ __forceinline__ unsigned cvt_pk_bf16(float lo, float hi) { unsigned r; asm volatile("v_cvt_pk_bf16_f32 %0, %1, %2" : "=v"(r) : "v"(lo), "v"(hi)); return r; }
;     __device__ __forceinline__ void operator()(const f32x4 (&acc)[2][2][4][2], const Unit& u, int wr, int wc, int fr, int fq) const {
;     ...
;                 const int row = row0 + ai * HALF + m * 16; const float rs = 1.0f / sqrtf(__hip_atomic_load(ss2 + row, __ATOMIC_RELAXED, __HIP_MEMORY_SCOPE_AGENT) * (1.0f / 2048.0f) + EPSN);
;                 bf16_t* rowp = H + (size_t)row * DFF + col0;
; #pragma unroll
;                 for (int bj = 0; bj < 2; ++bj) {
;                     f32x4 v0 = acc[ai][bj][m][0] * rs, v1 = acc[ai][bj][m][1] * rs;
; #pragma unroll
;                     for (int j = 0; j < 4; ++j) { v0[j] = fmaxf(v0[j], 0.f); v0[j] *= v0[j]; v1[j] = fmaxf(v1[j], 0.f); v1[j] *= v1[j]; }
;                     u32x4 w; w.x = cvt_pk_bf16(v0[0], v0[1]); w.y = cvt_pk_bf16(v0[2], v0[3]); w.z = cvt_pk_bf16(v1[0], v1[1]); w.w = cvt_pk_bf16(v1[2], v1[3]);
;                     *(u32x4*)(rowp + bj * HALF) = w;
	v_fmamk_f32 v16, v234, 0x3a000000, v158
	v_mul_f32_e32 v17, 0x4f800000, v16
	v_cmp_gt_f32_e32 vcc, s77, v16
	s_nop 1
	v_cndmask_b32_e32 v18, v16, v17, vcc
	v_sqrt_f32_e32 v19, v18
	v_lshl_add_u64 v[16:17], v[146:147], 0, s[46:47]
	v_add_u32_e32 v20, -1, v19
	v_add_u32_e32 v21, 1, v19
	v_fma_f32 v22, -v20, v19, v18
	v_fma_f32 v23, -v21, v19, v18
	v_cmp_ge_f32_e64 s[6:7], 0, v22
	s_nop 1
	v_cndmask_b32_e64 v19, v19, v20, s[6:7]
	v_cmp_lt_f32_e64 s[6:7], 0, v23
	s_nop 1
	v_cndmask_b32_e64 v19, v19, v21, s[6:7]
	v_mul_f32_e32 v20, 0x37800000, v19
	v_cndmask_b32_e32 v19, v19, v20, vcc
	v_cmp_class_f32_e32 vcc, v18, v159
	s_nop 1
	v_cndmask_b32_e32 v20, v19, v18, vcc
	v_div_scale_f32 v21, s[0:1], v20, v20, 1.0
	v_rcp_f32_e32 v22, v21
	v_add_co_u32_e32 v18, vcc, s81, v146
	v_fma_f32 v24, -v21, v22, 1.0
	s_nop 0
	v_addc_co_u32_e32 v19, vcc, 0, v147, vcc
	v_div_scale_f32 v23, vcc, 1.0, v20, 1.0
	v_fmac_f32_e32 v22, v24, v22
	v_mul_f32_e32 v24, v23, v22
	v_fma_f32 v25, -v21, v24, v23
	v_fmac_f32_e32 v24, v25, v22
	v_fma_f32 v21, -v21, v24, v23
	v_div_fmas_f32 v21, v21, v22, v24
	v_div_fixup_f32 v20, v21, v20, 1.0
	v_pk_mul_f32 v[14:15], v[14:15], v[20:21] op_sel_hi:[1,0]
	v_pk_mul_f32 v[12:13], v[12:13], v[20:21] op_sel_hi:[1,0]
	v_pk_mul_f32 v[10:11], v[10:11], v[20:21] op_sel_hi:[1,0]
	v_pk_mul_f32 v[8:9], v[8:9], v[20:21] op_sel_hi:[1,0]
	v_pk_mul_f32 v[2:3], v[2:3], v[20:21] op_sel_hi:[1,0]
	v_pk_mul_f32 v[0:1], v[0:1], v[20:21] op_sel_hi:[1,0]
	v_pk_mul_f32 v[6:7], v[6:7], v[20:21] op_sel_hi:[1,0]
	v_pk_mul_f32 v[4:5], v[4:5], v[20:21] op_sel_hi:[1,0]
	v_max_f32_e32 v12, 0, v12
	v_max_f32_e32 v8, 0, v8
	v_max_f32_e32 v13, 0, v13
	v_max_f32_e32 v9, 0, v9
	v_max_f32_e32 v14, 0, v14
	v_max_f32_e32 v10, 0, v10
	v_max_f32_e32 v15, 0, v15
	v_max_f32_e32 v11, 0, v11
	v_max_f32_e32 v0, 0, v0
	v_max_f32_e32 v1, 0, v1
	v_max_f32_e32 v2, 0, v2
	v_max_f32_e32 v3, 0, v3
	s_andn2_b64 vcc, exec, s[4:5]
	v_max_f32_e32 v4, 0, v4
	v_max_f32_e32 v5, 0, v5
	v_max_f32_e32 v6, 0, v6
	v_max_f32_e32 v7, 0, v7
	v_mul_f32_e32 v12, v12, v12
	v_mul_f32_e32 v8, v8, v8
	v_mul_f32_e32 v13, v13, v13
	v_mul_f32_e32 v9, v9, v9
	v_mul_f32_e32 v14, v14, v14
	v_mul_f32_e32 v10, v10, v10
	v_mul_f32_e32 v15, v15, v15
	v_mul_f32_e32 v11, v11, v11
	v_mul_f32_e32 v20, v0, v0
	v_mul_f32_e32 v21, v1, v1
	v_mul_f32_e32 v22, v2, v2
	v_mul_f32_e32 v23, v3, v3
	v_cvt_pk_bf16_f32 v0, v12, v13
	v_cvt_pk_bf16_f32 v1, v14, v15
	v_cvt_pk_bf16_f32 v2, v8, v9
	v_cvt_pk_bf16_f32 v3, v10, v11
	s_mov_b64 s[4:5], -1
	v_mul_f32_e32 v4, v4, v4
	v_mul_f32_e32 v5, v5, v5
	v_mul_f32_e32 v6, v6, v6
	v_mul_f32_e32 v7, v7, v7
	global_store_dwordx4 v[18:19], v[0:3], off
	s_nop 1
	v_cvt_pk_bf16_f32 v0, v4, v5
	v_cvt_pk_bf16_f32 v1, v6, v7
	v_cvt_pk_bf16_f32 v2, v20, v21
	v_cvt_pk_bf16_f32 v3, v22, v23
	global_store_dwordx4 v[16:17], v[0:3], off offset:256
	s_cbranch_vccnz .LBB0_1053
	s_andn2_b64 vcc, exec, s[22:23]
	s_cbranch_vccnz .LBB0_1052
	s_barrier
	s_branch .LBB0_1052
